# RET3 gate loads/output stores and kv-unit KVT stores made quad-row-contiguous by lane permutation
# speedup vs baseline: 1.0134x; 1.0134x over previous
.LBB0_973:
	s_bfe_u32 s52, s35, 0x30005
	s_and_b32 s53, s14, 0xfffff000
	s_and_b32 s54, s16, 0xf80
	v_cvt_f32_ubyte0_e32 v30, s52
	s_or_b32 s53, s53, s54
	v_sub_f32_e32 v30, 0xc0a00000, v30
	s_mul_hi_i32 s54, s53, 0x5c00
	s_mulk_i32 s53, 0x5c00
	v_cmp_gt_f32_e32 vcc, s18, v30
	s_add_u32 s53, s12, s53
	s_addc_u32 s58, s13, s54
	v_cndmask_b32_e32 v31, 0, v27, vcc
	s_lshl_b32 s54, s52, 8
	v_add_f32_e32 v30, v30, v31
	s_add_u32 s54, s53, s54
	v_exp_f32_e32 v32, v30
	s_addc_u32 s55, s58, 0
	v_mov_b32_e32 v15, v1
	s_and_b64 s[56:57], vcc, exec
	v_lshl_add_u64 v[30:31], s[54:55], 0, v[0:1]
	s_cselect_b32 s54, 0xffffffc0, 0
	v_lshl_add_u64 v[30:31], v[30:31], 0, v[14:15]
	v_ldexp_f32 v46, v32, s54
	v_lshl_add_u64 v[42:43], v[30:31], 0, s[8:9]
	v_add_co_u32_e32 v30, vcc, s26, v30
	v_sub_f32_e32 v46, 1.0, v46
	s_nop 0
	v_addc_co_u32_e32 v31, vcc, 0, v31, vcc
	v_cmp_gt_f32_e32 vcc, s19, v46
	s_and_b64 s[54:55], vcc, exec
	s_cselect_b32 s54, 32, 0
	s_lshl_b32 s52, s52, 9
	s_add_u32 s52, s53, s52
	v_ldexp_f32 v46, v46, s54
	s_addc_u32 s53, s58, 0
	v_log_f32_e32 v49, v46
	v_lshl_add_u64 v[46:47], s[52:53], 0, v[0:1]
	global_load_dwordx4 v[30:33], v[30:31], off offset:1024
	s_nop 0
	global_load_dwordx4 v[34:37], v[42:43], off offset:64
	global_load_dwordx4 v[38:41], v[42:43], off offset:128
	s_nop 0
	global_load_dwordx4 v[42:45], v[42:43], off offset:192
	v_lshl_add_u64 v[46:47], v[46:47], 0, v[14:15]
	v_cndmask_b32_e32 v48, 0, v28, vcc
	v_add_co_u32_e32 v74, vcc, s26, v46
	v_lshl_add_u64 v[62:63], v[46:47], 0, s[10:11]
	s_nop 0
	v_addc_co_u32_e32 v75, vcc, 0, v47, vcc
	v_sub_f32_e32 v15, v49, v48
	global_load_dwordx4 v[46:49], v[62:63], off offset:64
	global_load_dwordx4 v[50:53], v[62:63], off offset:128
	global_load_dwordx4 v[54:57], v[62:63], off offset:192
	global_load_dwordx4 v[58:61], v[62:63], off offset:256
	global_load_dwordx4 v[66:69], v[62:63], off offset:320
	global_load_dwordx4 v[70:73], v[62:63], off offset:384
	s_nop 0
	global_load_dwordx4 v[74:77], v[74:75], off offset:3072
	s_nop 0
	global_load_dwordx4 v[78:81], v[62:63], off offset:448
	v_mul_f32_e32 v62, v15, v16
	v_cmp_gt_f32_e32 vcc, s18, v62
	s_add_i32 s35, s35, s94
	s_add_i32 s14, s14, s15
	v_cndmask_b32_e32 v62, 0, v27, vcc
	v_fmac_f32_e32 v62, v15, v16
	v_exp_f32_e32 v62, v62
	v_cndmask_b32_e32 v15, 0, v29, vcc
	s_add_i32 s16, s16, s17
	v_lshl_add_u64 v[126:127], s[50:51], 0, v[4:5]
	v_ldexp_f32 v62, v62, v15
	v_lshl_add_u64 v[154:155], s[50:51], 0, v[6:7]
	v_lshl_add_u64 v[156:157], s[50:51], 0, v[8:9]
	v_lshl_add_u64 v[158:159], s[50:51], 0, v[10:11]
	v_lshl_add_u64 v[4:5], v[4:5], 0, s[4:5]
	v_lshl_add_u64 v[6:7], v[6:7], 0, s[4:5]
	v_lshl_add_u64 v[8:9], v[8:9], 0, s[4:5]
	v_lshl_add_u64 v[10:11], v[10:11], 0, s[4:5]
	s_cmpk_gt_i32 s35, 0x1ff
	s_waitcnt vmcnt(11)
	v_lshlrev_b32_e32 v82, 16, v30
	v_and_b32_e32 v83, 0xffff0000, v30
	v_lshlrev_b32_e32 v30, 16, v31
	v_and_b32_e32 v31, 0xffff0000, v31
	v_lshlrev_b32_e32 v84, 16, v32
	v_and_b32_e32 v85, 0xffff0000, v32
	v_lshlrev_b32_e32 v32, 16, v33
	v_and_b32_e32 v33, 0xffff0000, v33
	s_waitcnt vmcnt(10)
	v_lshlrev_b32_e32 v86, 16, v34
	v_and_b32_e32 v87, 0xffff0000, v34
	v_lshlrev_b32_e32 v34, 16, v35
	v_and_b32_e32 v35, 0xffff0000, v35
	v_lshlrev_b32_e32 v88, 16, v36
	v_and_b32_e32 v89, 0xffff0000, v36
	v_lshlrev_b32_e32 v36, 16, v37
	v_and_b32_e32 v37, 0xffff0000, v37
	s_waitcnt vmcnt(9)
	v_lshlrev_b32_e32 v90, 16, v38
	v_and_b32_e32 v91, 0xffff0000, v38
	v_lshlrev_b32_e32 v38, 16, v39
	v_and_b32_e32 v39, 0xffff0000, v39
	v_lshlrev_b32_e32 v92, 16, v40
	v_and_b32_e32 v93, 0xffff0000, v40
	v_lshlrev_b32_e32 v40, 16, v41
	v_and_b32_e32 v41, 0xffff0000, v41
	s_waitcnt vmcnt(8)
	v_lshlrev_b32_e32 v94, 16, v42
	v_and_b32_e32 v95, 0xffff0000, v42
	v_lshlrev_b32_e32 v42, 16, v43
	v_and_b32_e32 v43, 0xffff0000, v43
	v_lshlrev_b32_e32 v96, 16, v44
	v_and_b32_e32 v97, 0xffff0000, v44
	v_lshlrev_b32_e32 v44, 16, v45
	v_and_b32_e32 v45, 0xffff0000, v45
	v_pk_mul_f32 v[82:83], v[62:63], v[82:83] op_sel_hi:[0,1]
	v_pk_mul_f32 v[30:31], v[62:63], v[30:31] op_sel_hi:[0,1]
	v_pk_mul_f32 v[84:85], v[62:63], v[84:85] op_sel_hi:[0,1]
	v_pk_mul_f32 v[32:33], v[62:63], v[32:33] op_sel_hi:[0,1]
	v_pk_mul_f32 v[86:87], v[62:63], v[86:87] op_sel_hi:[0,1]
	v_pk_mul_f32 v[34:35], v[62:63], v[34:35] op_sel_hi:[0,1]
	v_pk_mul_f32 v[88:89], v[62:63], v[88:89] op_sel_hi:[0,1]
	v_pk_mul_f32 v[36:37], v[62:63], v[36:37] op_sel_hi:[0,1]
	v_pk_mul_f32 v[90:91], v[62:63], v[90:91] op_sel_hi:[0,1]
	v_pk_mul_f32 v[38:39], v[62:63], v[38:39] op_sel_hi:[0,1]
	v_pk_mul_f32 v[92:93], v[62:63], v[92:93] op_sel_hi:[0,1]
	v_pk_mul_f32 v[40:41], v[62:63], v[40:41] op_sel_hi:[0,1]
	v_pk_mul_f32 v[94:95], v[62:63], v[94:95] op_sel_hi:[0,1]
	v_pk_mul_f32 v[42:43], v[62:63], v[42:43] op_sel_hi:[0,1]
	v_pk_mul_f32 v[96:97], v[62:63], v[96:97] op_sel_hi:[0,1]
	v_pk_mul_f32 v[44:45], v[62:63], v[44:45] op_sel_hi:[0,1]
	v_cvt_pk_bf16_f32 v15, v82, v83
	v_cvt_pk_bf16_f32 v30, v30, v31
	v_cvt_pk_bf16_f32 v31, v84, v85
	v_cvt_pk_bf16_f32 v32, v32, v33
	v_cvt_pk_bf16_f32 v33, v86, v87
	v_cvt_pk_bf16_f32 v34, v34, v35
	v_cvt_pk_bf16_f32 v35, v88, v89
	v_cvt_pk_bf16_f32 v36, v36, v37
	v_cvt_pk_bf16_f32 v37, v90, v91
	v_cvt_pk_bf16_f32 v38, v38, v39
	v_cvt_pk_bf16_f32 v39, v92, v93
	v_cvt_pk_bf16_f32 v40, v40, v41
	v_cvt_pk_bf16_f32 v41, v94, v95
	v_cvt_pk_bf16_f32 v42, v42, v43
	v_cvt_pk_bf16_f32 v43, v96, v97
	v_cvt_pk_bf16_f32 v44, v44, v45
	ds_write_b16 v18, v15
	ds_write_b16_d16_hi v18, v15 offset:272
	ds_write_b16 v18, v30 offset:544
	ds_write_b16_d16_hi v18, v30 offset:816
	ds_write_b16 v18, v31 offset:1088
	ds_write_b16_d16_hi v18, v31 offset:1360
	ds_write_b16 v18, v32 offset:1632
	ds_write_b16_d16_hi v18, v32 offset:1904
	ds_write_b16 v18, v33 offset:8704
	ds_write_b16_d16_hi v18, v33 offset:8976
	ds_write_b16 v18, v34 offset:9248
	ds_write_b16_d16_hi v18, v34 offset:9520
	ds_write_b16 v18, v35 offset:9792
	ds_write_b16_d16_hi v18, v35 offset:10064
	ds_write_b16 v18, v36 offset:10336
	ds_write_b16_d16_hi v18, v36 offset:10608
	ds_write_b16 v18, v37 offset:17408
	ds_write_b16_d16_hi v18, v37 offset:17680
	ds_write_b16 v18, v38 offset:17952
	ds_write_b16_d16_hi v18, v38 offset:18224
	ds_write_b16 v18, v39 offset:18496
	ds_write_b16_d16_hi v18, v39 offset:18768
	ds_write_b16 v18, v40 offset:19040
	ds_write_b16_d16_hi v18, v40 offset:19312
	ds_write_b16 v18, v41 offset:26112
	ds_write_b16_d16_hi v18, v41 offset:26384
	ds_write_b16 v18, v42 offset:26656
	ds_write_b16_d16_hi v18, v42 offset:26928
	ds_write_b16 v18, v43 offset:27200
	ds_write_b16_d16_hi v18, v43 offset:27472
	ds_write_b16 v18, v44 offset:27744
	ds_write_b16_d16_hi v18, v44 offset:28016
	s_waitcnt vmcnt(1)
	ds_write_b16 v18, v74 offset:34816
	ds_write_b16_d16_hi v18, v74 offset:35088
	ds_write_b16 v18, v75 offset:35360
	ds_write_b16_d16_hi v18, v75 offset:35632
	ds_write_b16 v18, v76 offset:35904
	ds_write_b16_d16_hi v18, v76 offset:36176
	ds_write_b16 v18, v77 offset:36448
	ds_write_b16_d16_hi v18, v77 offset:36720
	ds_write_b16 v18, v46 offset:43520
	ds_write_b16_d16_hi v18, v46 offset:43792
	ds_write_b16 v18, v47 offset:44064
	ds_write_b16_d16_hi v18, v47 offset:44336
	ds_write_b16 v18, v48 offset:44608
	ds_write_b16_d16_hi v18, v48 offset:44880
	ds_write_b16 v18, v49 offset:45152
	ds_write_b16_d16_hi v18, v49 offset:45424
	ds_write_b16 v18, v50 offset:52224
	ds_write_b16_d16_hi v18, v50 offset:52496
	ds_write_b16 v18, v51 offset:52768
	ds_write_b16_d16_hi v18, v51 offset:53040
	ds_write_b16 v18, v52 offset:53312
	ds_write_b16_d16_hi v18, v52 offset:53584
	ds_write_b16 v18, v53 offset:53856
	ds_write_b16_d16_hi v18, v53 offset:54128
	ds_write_b16 v18, v54 offset:60928
	ds_write_b16_d16_hi v18, v54 offset:61200
	ds_write_b16 v18, v55 offset:61472
	ds_write_b16_d16_hi v18, v55 offset:61744
	ds_write_b16 v18, v56 offset:62016
	ds_write_b16_d16_hi v18, v56 offset:62288
	ds_write_b16 v18, v57 offset:62560
	ds_write_b16_d16_hi v18, v57 offset:62832
	ds_write_b16 v19, v58 offset:34816
	ds_write_b16_d16_hi v19, v58 offset:35088
	ds_write_b16 v19, v59 offset:35360
	ds_write_b16_d16_hi v19, v59 offset:35632
	ds_write_b16 v19, v60 offset:35904
	ds_write_b16_d16_hi v19, v60 offset:36176
	ds_write_b16 v19, v61 offset:36448
	ds_write_b16_d16_hi v19, v61 offset:36720
	ds_write_b16 v19, v66 offset:43520
	ds_write_b16_d16_hi v19, v66 offset:43792
	ds_write_b16 v19, v67 offset:44064
	ds_write_b16_d16_hi v19, v67 offset:44336
	ds_write_b16 v19, v68 offset:44608
	ds_write_b16_d16_hi v19, v68 offset:44880
	ds_write_b16 v19, v69 offset:45152
	ds_write_b16_d16_hi v19, v69 offset:45424
	ds_write_b16 v19, v70 offset:52224
	ds_write_b16_d16_hi v19, v70 offset:52496
	ds_write_b16 v19, v71 offset:52768
	ds_write_b16_d16_hi v19, v71 offset:53040
	ds_write_b16 v19, v72 offset:53312
	ds_write_b16_d16_hi v19, v72 offset:53584
	ds_write_b16 v19, v73 offset:53856
	ds_write_b16_d16_hi v19, v73 offset:54128
	s_waitcnt vmcnt(0)
	ds_write_b16 v19, v78 offset:60928
	ds_write_b16_d16_hi v19, v78 offset:61200
	ds_write_b16 v19, v79 offset:61472
	ds_write_b16_d16_hi v19, v79 offset:61744
	ds_write_b16 v19, v80 offset:62016
	ds_write_b16_d16_hi v19, v80 offset:62288
	ds_write_b16 v19, v81 offset:62560
	ds_write_b16_d16_hi v19, v81 offset:62832
	s_waitcnt lgkmcnt(0)
	s_barrier
	ds_read_b128 v[30:33], v26
	ds_read_b128 v[34:37], v17 offset:34816
	ds_read_b128 v[38:41], v17 offset:34880
	ds_read_b128 v[42:45], v26 offset:64
	ds_read_b128 v[50:53], v17 offset:39168
	ds_read_b128 v[54:57], v17 offset:39232
	ds_read_b128 v[58:61], v26 offset:4352
	ds_read_b128 v[66:69], v26 offset:4416
	ds_read_b128 v[74:77], v26 offset:8704
	ds_read_b128 v[78:81], v26 offset:8768
	ds_read_b128 v[86:89], v26 offset:13056
	ds_read_b128 v[90:93], v26 offset:13120
	ds_read_b128 v[98:101], v26 offset:17408
	ds_read_b128 v[102:105], v26 offset:17472
	ds_read_b128 v[110:113], v26 offset:21760
	ds_read_b128 v[114:117], v26 offset:21824
	ds_read_b128 v[122:125], v26 offset:26112
	ds_read_b128 v[130:133], v26 offset:26176
	ds_read_b128 v[138:141], v26 offset:30464
	ds_read_b128 v[142:145], v26 offset:30528
	s_waitcnt lgkmcnt(14)
	v_mfma_f32_16x16x32_bf16 v[46:49], v[30:33], v[34:37], 0
	v_lshl_add_u64 v[62:63], s[50:51], 0, v[2:3]
	v_add_co_u32_e32 v160, vcc, s27, v62
	v_mfma_f32_16x16x32_bf16 v[30:33], v[30:33], v[50:53], 0
	s_nop 0
	v_addc_co_u32_e32 v161, vcc, 0, v63, vcc
	v_add_co_u32_e32 v162, vcc, s28, v62
	s_waitcnt lgkmcnt(13)
	v_mfma_f32_16x16x32_bf16 v[70:73], v[58:61], v[34:37], 0
	v_addc_co_u32_e32 v163, vcc, 0, v63, vcc
	v_add_co_u32_e32 v164, vcc, s29, v62
	v_mfma_f32_16x16x32_bf16 v[58:61], v[58:61], v[50:53], 0
	s_nop 0
	v_addc_co_u32_e32 v165, vcc, 0, v63, vcc
	v_add_co_u32_e32 v62, vcc, s30, v62
	s_waitcnt lgkmcnt(11)
	v_mfma_f32_16x16x32_bf16 v[82:85], v[74:77], v[34:37], 0
	v_addc_co_u32_e32 v63, vcc, 0, v63, vcc
	v_lshl_add_u64 v[2:3], v[2:3], 0, s[4:5]
	v_mfma_f32_16x16x32_bf16 v[74:77], v[74:77], v[50:53], 0
	s_waitcnt lgkmcnt(9)
	v_mfma_f32_16x16x32_bf16 v[94:97], v[86:89], v[34:37], 0
	v_mfma_f32_16x16x32_bf16 v[86:89], v[86:89], v[50:53], 0
	s_waitcnt lgkmcnt(7)
	v_mfma_f32_16x16x32_bf16 v[106:109], v[98:101], v[34:37], 0
	v_mfma_f32_16x16x32_bf16 v[98:101], v[98:101], v[50:53], 0
	s_waitcnt lgkmcnt(5)
	v_mfma_f32_16x16x32_bf16 v[118:121], v[110:113], v[34:37], 0
	s_waitcnt lgkmcnt(3)
	v_mfma_f32_16x16x32_bf16 v[134:137], v[122:125], v[34:37], 0
	s_waitcnt lgkmcnt(1)
	v_mfma_f32_16x16x32_bf16 v[34:37], v[138:141], v[34:37], 0
	v_mfma_f32_16x16x32_bf16 v[46:49], v[42:45], v[38:41], v[46:49]
	v_mfma_f32_16x16x32_bf16 v[30:33], v[42:45], v[54:57], v[30:33]
	v_mfma_f32_16x16x32_bf16 v[42:45], v[66:69], v[38:41], v[70:73]
	v_mfma_f32_16x16x32_bf16 v[58:61], v[66:69], v[54:57], v[58:61]
	v_mfma_f32_16x16x32_bf16 v[66:69], v[78:81], v[38:41], v[82:85]
	v_mfma_f32_16x16x32_bf16 v[70:73], v[78:81], v[54:57], v[74:77]
	v_mfma_f32_16x16x32_bf16 v[74:77], v[90:93], v[38:41], v[94:97]
	v_mfma_f32_16x16x32_bf16 v[78:81], v[90:93], v[54:57], v[86:89]
	v_mfma_f32_16x16x32_bf16 v[82:85], v[102:105], v[38:41], v[106:109]
	v_mfma_f32_16x16x32_bf16 v[86:89], v[102:105], v[54:57], v[98:101]
	v_mfma_f32_16x16x32_bf16 v[90:93], v[114:117], v[38:41], v[118:121]
	v_mfma_f32_16x16x32_bf16 v[98:101], v[130:133], v[38:41], v[134:137]
	s_waitcnt lgkmcnt(0)
	v_mfma_f32_16x16x32_bf16 v[34:37], v[142:145], v[38:41], v[34:37]
	ds_read_b128 v[38:41], v26 offset:128
	v_mfma_f32_16x16x32_bf16 v[110:113], v[110:113], v[50:53], 0
	v_mfma_f32_16x16x32_bf16 v[122:125], v[122:125], v[50:53], 0
	v_mfma_f32_16x16x32_bf16 v[50:53], v[138:141], v[50:53], 0
	v_mfma_f32_16x16x32_bf16 v[94:97], v[114:117], v[54:57], v[110:113]
	v_mfma_f32_16x16x32_bf16 v[102:105], v[130:133], v[54:57], v[122:125]
	v_mfma_f32_16x16x32_bf16 v[50:53], v[142:145], v[54:57], v[50:53]
	ds_read_b128 v[54:57], v17 offset:34944
	ds_read_b128 v[106:109], v17 offset:35008
	s_nop 0
	ds_read_b128 v[110:113], v26 offset:192
	ds_read_b128 v[114:117], v17 offset:39296
	ds_read_b128 v[118:121], v17 offset:39360
	s_waitcnt lgkmcnt(4)
	v_mfma_f32_16x16x32_bf16 v[46:49], v[38:41], v[54:57], v[46:49]
	s_waitcnt lgkmcnt(1)
	v_mfma_f32_16x16x32_bf16 v[30:33], v[38:41], v[114:117], v[30:33]
	ds_read_b128 v[38:41], v26 offset:4480
	ds_read_b128 v[122:125], v26 offset:4544
	s_waitcnt lgkmcnt(1)
	v_mfma_f32_16x16x32_bf16 v[42:45], v[38:41], v[54:57], v[42:45]
	v_mfma_f32_16x16x32_bf16 v[38:41], v[38:41], v[114:117], v[58:61]
	s_nop 2
	ds_read_b128 v[58:61], v26 offset:8832
	ds_read_b128 v[130:133], v26 offset:8896
	s_waitcnt lgkmcnt(1)
	v_mfma_f32_16x16x32_bf16 v[66:69], v[58:61], v[54:57], v[66:69]
	v_mfma_f32_16x16x32_bf16 v[58:61], v[58:61], v[114:117], v[70:73]
	s_nop 2
	ds_read_b128 v[70:73], v26 offset:13184
	ds_read_b128 v[134:137], v26 offset:13248
	s_waitcnt lgkmcnt(1)
	v_mfma_f32_16x16x32_bf16 v[74:77], v[70:73], v[54:57], v[74:77]
	v_mfma_f32_16x16x32_bf16 v[70:73], v[70:73], v[114:117], v[78:81]
	s_nop 2
	ds_read_b128 v[78:81], v26 offset:17536
	ds_read_b128 v[138:141], v26 offset:17600
	s_waitcnt lgkmcnt(1)
	v_mfma_f32_16x16x32_bf16 v[82:85], v[78:81], v[54:57], v[82:85]
	v_mfma_f32_16x16x32_bf16 v[78:81], v[78:81], v[114:117], v[86:89]
	s_nop 2
	ds_read_b128 v[86:89], v26 offset:21888
	ds_read_b128 v[142:145], v26 offset:21952
	s_waitcnt lgkmcnt(1)
	v_mfma_f32_16x16x32_bf16 v[90:93], v[86:89], v[54:57], v[90:93]
	v_mfma_f32_16x16x32_bf16 v[86:89], v[86:89], v[114:117], v[94:97]
	s_nop 2
	ds_read_b128 v[94:97], v26 offset:26240
	ds_read_b128 v[146:149], v26 offset:26304
	s_waitcnt lgkmcnt(1)
	v_mfma_f32_16x16x32_bf16 v[98:101], v[94:97], v[54:57], v[98:101]
	v_mfma_f32_16x16x32_bf16 v[94:97], v[94:97], v[114:117], v[102:105]
	s_nop 2
	ds_read_b128 v[102:105], v26 offset:30592
	ds_read_b128 v[150:153], v26 offset:30656
	s_waitcnt lgkmcnt(1)
	v_mfma_f32_16x16x32_bf16 v[34:37], v[102:105], v[54:57], v[34:37]
	v_mfma_f32_16x16x32_bf16 v[50:53], v[102:105], v[114:117], v[50:53]
	v_lshl_add_u64 v[102:103], s[50:51], 0, v[12:13]
	v_add_co_u32_e32 v166, vcc, s31, v102
	v_mfma_f32_16x16x32_bf16 v[46:49], v[110:113], v[106:109], v[46:49]
	s_nop 0
	v_addc_co_u32_e32 v167, vcc, 0, v103, vcc
	v_add_co_u32_e32 v168, vcc, s33, v102
	v_mfma_f32_16x16x32_bf16 v[30:33], v[110:113], v[118:121], v[30:33]
	s_nop 0
	v_addc_co_u32_e32 v169, vcc, 0, v103, vcc
	v_lshl_add_u64 v[12:13], v[12:13], 0, s[6:7]
	v_mfma_f32_16x16x32_bf16 v[42:45], v[122:125], v[106:109], v[42:45]
	v_mfma_f32_16x16x32_bf16 v[38:41], v[122:125], v[118:121], v[38:41]
	v_mfma_f32_16x16x32_bf16 v[54:57], v[130:133], v[106:109], v[66:69]
	v_mfma_f32_16x16x32_bf16 v[58:61], v[130:133], v[118:121], v[58:61]
	v_mfma_f32_16x16x32_bf16 v[66:69], v[134:137], v[106:109], v[74:77]
	v_mfma_f32_16x16x32_bf16 v[70:73], v[134:137], v[118:121], v[70:73]
	v_mfma_f32_16x16x32_bf16 v[74:77], v[138:141], v[106:109], v[82:85]
	s_nop 2
	ds_read_b128 v[82:85], v20 offset:34816
	ds_read_b128 v[102:105], v20 offset:52224
	ds_read_b128 v[110:113], v21 offset:34816
	ds_read_b128 v[114:117], v22 offset:34816
	ds_read_b128 v[122:125], v24 offset:34816
	ds_read_b128 v[130:133], v23 offset:34816
	ds_read_b128 v[134:137], v23 offset:52224
	v_mfma_f32_16x16x32_bf16 v[78:81], v[138:141], v[118:121], v[78:81]
	ds_read_b128 v[138:141], v25 offset:34816
	s_waitcnt lgkmcnt(7)
	global_store_dwordx4 v[160:161], v[82:85], off
	s_waitcnt lgkmcnt(5)
	global_store_dwordx4 v[126:127], v[110:113], off
	global_store_dwordx4 v[162:163], v[102:105], off
	s_waitcnt lgkmcnt(4)
	global_store_dwordx4 v[154:155], v[114:117], off
	s_waitcnt lgkmcnt(2)
	global_store_dwordx4 v[164:165], v[130:133], off
	v_mfma_f32_16x16x32_bf16 v[90:93], v[142:145], v[106:109], v[90:93]
	global_store_dwordx4 v[156:157], v[122:125], off
	s_waitcnt lgkmcnt(1)
	global_store_dwordx4 v[62:63], v[134:137], off
	s_waitcnt lgkmcnt(0)
	global_store_dwordx4 v[158:159], v[138:141], off
	v_mfma_f32_16x16x32_bf16 v[86:89], v[142:145], v[118:121], v[86:89]
	v_mfma_f32_16x16x32_bf16 v[98:101], v[146:149], v[106:109], v[98:101]
	v_mfma_f32_16x16x32_bf16 v[82:85], v[146:149], v[118:121], v[94:97]
	v_mfma_f32_16x16x32_bf16 v[34:37], v[150:153], v[106:109], v[34:37]
	v_mfma_f32_16x16x32_bf16 v[50:53], v[150:153], v[118:121], v[50:53]
	global_store_dwordx4 v[166:167], v[46:49], off
	v_and_b32_e32 v254, 63, v128
	v_and_b32_e32 v255, 3, v254
	v_lshrrev_b32_e32 v254, 2, v254
	v_lshl_or_b32 v254, v255, 4, v254
	v_lshlrev_b32_e32 v254, 2, v254
	ds_bpermute_b32 v238, v254, v42
	ds_bpermute_b32 v239, v254, v43
	ds_bpermute_b32 v240, v254, v44
	ds_bpermute_b32 v241, v254, v45
	ds_bpermute_b32 v236, v254, v166
	ds_bpermute_b32 v237, v254, v167
	ds_bpermute_b32 v244, v254, v54
	ds_bpermute_b32 v245, v254, v55
	ds_bpermute_b32 v246, v254, v56
	ds_bpermute_b32 v247, v254, v57
	ds_bpermute_b32 v242, v254, v166
	ds_bpermute_b32 v243, v254, v167
	ds_bpermute_b32 v250, v254, v66
	ds_bpermute_b32 v251, v254, v67
	ds_bpermute_b32 v252, v254, v68
	ds_bpermute_b32 v253, v254, v69
	ds_bpermute_b32 v248, v254, v166
	ds_bpermute_b32 v249, v254, v167
	s_waitcnt lgkmcnt(12)
	global_store_dwordx4 v[236:237], v[238:241], off offset:64
	s_nop 0
	ds_bpermute_b32 v238, v254, v74
	ds_bpermute_b32 v239, v254, v75
	ds_bpermute_b32 v240, v254, v76
	ds_bpermute_b32 v241, v254, v77
	ds_bpermute_b32 v236, v254, v166
	ds_bpermute_b32 v237, v254, v167
	s_waitcnt lgkmcnt(12)
	global_store_dwordx4 v[242:243], v[244:247], off offset:128
	s_nop 0
	ds_bpermute_b32 v244, v254, v90
	ds_bpermute_b32 v245, v254, v91
	ds_bpermute_b32 v246, v254, v92
	ds_bpermute_b32 v247, v254, v93
	ds_bpermute_b32 v242, v254, v166
	ds_bpermute_b32 v243, v254, v167
	s_waitcnt lgkmcnt(12)
	global_store_dwordx4 v[248:249], v[250:253], off offset:192
	s_nop 0
	ds_bpermute_b32 v250, v254, v98
	ds_bpermute_b32 v251, v254, v99
	ds_bpermute_b32 v252, v254, v100
	ds_bpermute_b32 v253, v254, v101
	ds_bpermute_b32 v248, v254, v166
	ds_bpermute_b32 v249, v254, v167
	s_waitcnt lgkmcnt(12)
	global_store_dwordx4 v[236:237], v[238:241], off offset:256
	s_nop 0
	ds_bpermute_b32 v238, v254, v34
	ds_bpermute_b32 v239, v254, v35
	ds_bpermute_b32 v240, v254, v36
	ds_bpermute_b32 v241, v254, v37
	ds_bpermute_b32 v236, v254, v166
	ds_bpermute_b32 v237, v254, v167
	s_waitcnt lgkmcnt(12)
	global_store_dwordx4 v[242:243], v[244:247], off offset:320
	s_nop 0
	ds_bpermute_b32 v244, v254, v30
	ds_bpermute_b32 v245, v254, v31
	ds_bpermute_b32 v246, v254, v32
	ds_bpermute_b32 v247, v254, v33
	ds_bpermute_b32 v242, v254, v168
	ds_bpermute_b32 v243, v254, v169
	s_waitcnt lgkmcnt(12)
	global_store_dwordx4 v[248:249], v[250:253], off offset:384
	s_nop 0
	ds_bpermute_b32 v250, v254, v38
	ds_bpermute_b32 v251, v254, v39
	ds_bpermute_b32 v252, v254, v40
	ds_bpermute_b32 v253, v254, v41
	ds_bpermute_b32 v248, v254, v168
	ds_bpermute_b32 v249, v254, v169
	s_waitcnt lgkmcnt(12)
	global_store_dwordx4 v[236:237], v[238:241], off offset:448
	s_nop 0
	ds_bpermute_b32 v238, v254, v58
	ds_bpermute_b32 v239, v254, v59
	ds_bpermute_b32 v240, v254, v60
	ds_bpermute_b32 v241, v254, v61
	ds_bpermute_b32 v236, v254, v168
	ds_bpermute_b32 v237, v254, v169
	s_waitcnt lgkmcnt(12)
	global_store_dwordx4 v[242:243], v[244:247], off
	s_nop 0
	ds_bpermute_b32 v244, v254, v70
	ds_bpermute_b32 v245, v254, v71
	ds_bpermute_b32 v246, v254, v72
	ds_bpermute_b32 v247, v254, v73
	ds_bpermute_b32 v242, v254, v168
	ds_bpermute_b32 v243, v254, v169
	s_waitcnt lgkmcnt(12)
	global_store_dwordx4 v[248:249], v[250:253], off offset:64
	s_nop 0
	ds_bpermute_b32 v250, v254, v78
	ds_bpermute_b32 v251, v254, v79
	ds_bpermute_b32 v252, v254, v80
	ds_bpermute_b32 v253, v254, v81
	ds_bpermute_b32 v248, v254, v168
	ds_bpermute_b32 v249, v254, v169
	s_waitcnt lgkmcnt(12)
	global_store_dwordx4 v[236:237], v[238:241], off offset:128
	s_nop 0
	ds_bpermute_b32 v238, v254, v86
	ds_bpermute_b32 v239, v254, v87
	ds_bpermute_b32 v240, v254, v88
	ds_bpermute_b32 v241, v254, v89
	ds_bpermute_b32 v236, v254, v168
	ds_bpermute_b32 v237, v254, v169
	s_waitcnt lgkmcnt(12)
	global_store_dwordx4 v[242:243], v[244:247], off offset:192
	s_nop 0
	ds_bpermute_b32 v244, v254, v82
	ds_bpermute_b32 v245, v254, v83
	ds_bpermute_b32 v246, v254, v84
	ds_bpermute_b32 v247, v254, v85
	ds_bpermute_b32 v242, v254, v168
	ds_bpermute_b32 v243, v254, v169
	s_waitcnt lgkmcnt(12)
	global_store_dwordx4 v[248:249], v[250:253], off offset:256
	s_nop 0
	ds_bpermute_b32 v250, v254, v50
	ds_bpermute_b32 v251, v254, v51
	ds_bpermute_b32 v252, v254, v52
	ds_bpermute_b32 v253, v254, v53
	ds_bpermute_b32 v248, v254, v168
	ds_bpermute_b32 v249, v254, v169
	s_waitcnt lgkmcnt(12)
	global_store_dwordx4 v[236:237], v[238:241], off offset:320
	s_waitcnt lgkmcnt(6)
	global_store_dwordx4 v[242:243], v[244:247], off offset:384
	s_waitcnt lgkmcnt(0)
	global_store_dwordx4 v[248:249], v[250:253], off offset:448
	s_barrier
	s_cbranch_scc0 .LBB0_973

.LBB0_1212:
	s_cmpk_gt_i32 s34, 0x1ff
	s_cbranch_scc1 .LBB0_1326
	v_and_b32_e32 v0, 63, v128
	v_and_b32_e32 v1, 15, v0
	v_lshrrev_b32_e32 v2, 4, v0
	v_readfirstlane_b32 s65, v128
	s_lshr_b32 s65, s65, 6
	s_and_b32 s80, s65, 3
	s_lshl_b32 s80, s80, 2
	v_add_u32_e32 v4, s80, v2
	v_xor_b32_e32 v4, v1, v4
	v_lshlrev_b32_e32 v4, 4, v4
	v_lshl_add_u32 v18, v2, 8, v4
	v_mov_b32_e32 v19, 0
	s_movk_i32 s81, 0x5c00
	v_mul_u32_u24_e32 v5, s81, v2
	v_add_u32_e32 v138, v5, v4
	v_mov_b32_e32 v139, 0
	v_lshlrev_b32_e32 v5, 8, v1
	v_add_u32_e32 v6, 0, v2
	v_xor_b32_e32 v6, v6, v1
	v_lshl_add_u32 v142, v6, 4, v5
	v_add_u32_e32 v146, 0x10000, v142
	v_add_u32_e32 v6, 4, v2
	v_xor_b32_e32 v6, v6, v1
	v_lshl_add_u32 v143, v6, 4, v5
	v_add_u32_e32 v147, 0x10000, v143
	v_add_u32_e32 v6, 8, v2
	v_xor_b32_e32 v6, v6, v1
	v_lshl_add_u32 v144, v6, 4, v5
	v_add_u32_e32 v148, 0x10000, v144
	v_add_u32_e32 v6, 12, v2
	v_xor_b32_e32 v6, v6, v1
	v_lshl_add_u32 v145, v6, 4, v5
	v_add_u32_e32 v149, 0x10000, v145
	v_lshrrev_b32_e32 v6, 1, v2
	v_and_b32_e32 v7, 1, v2
	v_lshlrev_b32_e32 v7, 3, v7
	v_add_u32_e32 v7, v7, v5
	v_add_u32_e32 v7, 0x10000, v7
	v_add_u32_e32 v8, 0, v6
	v_xor_b32_e32 v8, v8, v1
	v_lshl_add_u32 v150, v8, 4, v7
	v_add_u32_e32 v8, 2, v6
	v_xor_b32_e32 v8, v8, v1
	v_lshl_add_u32 v154, v8, 4, v7
	v_add_u32_e32 v8, 4, v6
	v_xor_b32_e32 v8, v8, v1
	v_lshl_add_u32 v151, v8, 4, v7
	v_add_u32_e32 v8, 6, v6
	v_xor_b32_e32 v8, v8, v1
	v_lshl_add_u32 v155, v8, 4, v7
	v_add_u32_e32 v8, 8, v6
	v_xor_b32_e32 v8, v8, v1
	v_lshl_add_u32 v152, v8, 4, v7
	v_add_u32_e32 v8, 10, v6
	v_xor_b32_e32 v8, v8, v1
	v_lshl_add_u32 v156, v8, 4, v7
	v_add_u32_e32 v8, 12, v6
	v_xor_b32_e32 v8, v8, v1
	v_lshl_add_u32 v153, v8, 4, v7
	v_add_u32_e32 v8, 14, v6
	v_xor_b32_e32 v8, v8, v1
	v_lshl_add_u32 v157, v8, 4, v7
	v_mul_u32_u24_e32 v6, s81, v1
	s_mul_i32 s82, s65, 0x5c000
	v_lshl_add_u32 v7, v2, 4, v6
	v_add_u32_e32 v9, s82, v7
	v_lshrrev_b32_e32 v7, 2, v0
	v_and_b32_e32 v5, 3, v0
	v_lshlrev_b32_e32 v5, 3, v5
	v_mul_u32_u24_e32 v6, s81, v7
	v_add3_u32 v140, v6, v5, s82
	s_lshl_b32 s83, s65, 16
	v_lshl_add_u32 v7, v7, 12, v5
	v_add_u32_e32 v124, s83, v7
	s_lshl_b32 s83, s65, 4
	v_lshlrev_b32_e32 v8, 2, v2
	v_sub_u32_e32 v8, v1, v8
	v_add_u32_e32 v8, s83, v8
	v_cvt_f32_i32_e32 v125, v8
	v_add_u32_e32 v8, s83, v1
	v_add_u32_e32 v8, 1, v8
	v_cvt_f32_i32_e32 v129, v8
	v_xor_b32_e32 v8, 16, v0
	v_lshlrev_b32_e32 v127, 2, v8
	v_xor_b32_e32 v8, 32, v0
	v_lshlrev_b32_e32 v11, 2, v8
	s_add_u32 s52, s50, 0x14705000
	s_addc_u32 s53, s51, 0
	s_add_u32 s54, s50, 0x24c05000
	s_addc_u32 s55, s51, 0
	s_add_u32 s56, s50, 0x26c05000
	s_addc_u32 s57, s51, 0
	s_add_u32 s58, s50, 0x22805000
	s_addc_u32 s59, s51, 0
	s_lshl_b32 s67, s65, 10
	s_mov_b32 s64, s34
.LR3_unit:
	s_and_b32 s80, s64, 31
	s_lshr_b32 s81, s64, 5
	s_and_b32 s66, s81, 7
	s_lshr_b32 s81, s81, 3
	s_lshl_b32 s81, s81, 12
	s_lshl_b32 s80, s80, 7
	s_add_u32 s80, s80, s81
	s_mul_i32 s82, s80, 0x5c00
	s_lshl_b32 s83, s66, 8
	s_add_u32 s82, s82, s83
	s_add_u32 s82, s82, 0xc00
	s_add_u32 s68, s52, s82
	s_addc_u32 s69, s53, 0
	s_add_u32 s84, s83, 0x2000
	s_add_u32 s72, s68, s84
	s_addc_u32 s73, s69, 0
	s_lshl_b32 s84, s80, 12
	s_lshl_b32 s85, s66, 9
	s_add_u32 s84, s84, s85
	s_add_u32 s74, s58, s84
	s_addc_u32 s75, s59, 0
	s_mul_i32 s84, s65, 0x17000
	s_add_u32 s84, s84, 0x800
	s_add_u32 s86, s68, s84
	s_addc_u32 s87, s69, 0
	s_add_u32 s88, s67, 0x10000
	s_mov_b32 m0, s88
	v_lshl_add_u64 v[4:5], s[86:87], 0, v[138:139]
	global_load_lds_dwordx4 v[4:5], off
	s_add_u32 s86, s86, 0xb8000
	s_addc_u32 s87, s87, 0
	s_add_u32 s88, s88, 0x2000
	s_mov_b32 m0, s88
	v_lshl_add_u64 v[4:5], s[86:87], 0, v[138:139]
	global_load_lds_dwordx4 v[4:5], off
	s_add_u32 s86, s86, 0xb8000
	s_addc_u32 s87, s87, 0
	s_add_u32 s88, s88, 0x2000
	s_mov_b32 m0, s88
	v_lshl_add_u64 v[4:5], s[86:87], 0, v[138:139]
	global_load_lds_dwordx4 v[4:5], off
	s_add_u32 s86, s86, 0xb8000
	s_addc_u32 s87, s87, 0
	s_add_u32 s88, s88, 0x2000
	s_mov_b32 m0, s88
	v_lshl_add_u64 v[4:5], s[86:87], 0, v[138:139]
	global_load_lds_dwordx4 v[4:5], off
	global_load_dwordx4 v[20:23], v9, s[68:69] offset:0
	global_load_dwordx4 v[24:27], v9, s[68:69] offset:64
	global_load_dwordx4 v[28:31], v9, s[68:69] offset:128
	global_load_dwordx4 v[32:35], v9, s[68:69] offset:192
	s_lshl_b32 s84, s64, 16
	s_add_u32 s84, s84, s67
	s_add_u32 s76, s54, s84
	s_addc_u32 s77, s55, 0
	s_add_u32 s78, s56, s84
	s_addc_u32 s79, s57, 0
	s_mov_b32 s88, s67
	s_mov_b32 m0, s88
	v_lshl_add_u64 v[4:5], s[76:77], 0, v[18:19]
	global_load_lds_dwordx4 v[4:5], off
	s_add_u32 s76, s76, 0x2000
	s_addc_u32 s77, s77, 0
	s_add_u32 s88, s88, 0x2000
	s_mov_b32 m0, s88
	v_lshl_add_u64 v[4:5], s[76:77], 0, v[18:19]
	global_load_lds_dwordx4 v[4:5], off
	s_add_u32 s76, s76, 0x2000
	s_addc_u32 s77, s77, 0
	s_add_u32 s88, s88, 0x2000
	s_mov_b32 m0, s88
	v_lshl_add_u64 v[4:5], s[76:77], 0, v[18:19]
	global_load_lds_dwordx4 v[4:5], off
	s_add_u32 s76, s76, 0x2000
	s_addc_u32 s77, s77, 0
	s_add_u32 s88, s88, 0x2000
	s_mov_b32 m0, s88
	v_lshl_add_u64 v[4:5], s[76:77], 0, v[18:19]
	global_load_lds_dwordx4 v[4:5], off
	s_add_u32 s76, s76, 0x2000
	s_addc_u32 s77, s77, 0
	s_add_u32 s88, s88, 0x2000
	s_mov_b32 m0, s88
	v_lshl_add_u64 v[4:5], s[76:77], 0, v[18:19]
	global_load_lds_dwordx4 v[4:5], off
	s_add_u32 s76, s76, 0x2000
	s_addc_u32 s77, s77, 0
	s_add_u32 s88, s88, 0x2000
	s_mov_b32 m0, s88
	v_lshl_add_u64 v[4:5], s[76:77], 0, v[18:19]
	global_load_lds_dwordx4 v[4:5], off
	s_add_u32 s76, s76, 0x2000
	s_addc_u32 s77, s77, 0
	s_add_u32 s88, s88, 0x2000
	s_mov_b32 m0, s88
	v_lshl_add_u64 v[4:5], s[76:77], 0, v[18:19]
	global_load_lds_dwordx4 v[4:5], off
	s_add_u32 s76, s76, 0x2000
	s_addc_u32 s77, s77, 0
	s_add_u32 s88, s88, 0x2000
	s_mov_b32 m0, s88
	v_lshl_add_u64 v[4:5], s[76:77], 0, v[18:19]
	global_load_lds_dwordx4 v[4:5], off
	s_sub_i32 s85, -5, s66
	v_cvt_f32_i32_e32 v4, s85
	v_exp_f32_e32 v4, v4
	s_nop 0
	v_sub_f32_e32 v4, 1.0, v4
	v_log_f32_e32 v16, v4
	s_nop 0
	v_mul_f32_e32 v126, v129, v16
	v_exp_f32_e32 v126, v126
	s_waitcnt vmcnt(8)
	s_barrier
	ds_read_b128 v[52:55], v146 offset:0
	ds_read_b128 v[56:59], v147 offset:0
	ds_read_b128 v[60:63], v148 offset:0
	ds_read_b128 v[64:67], v149 offset:0
	ds_read_b128 v[68:71], v146 offset:4096
	ds_read_b128 v[72:75], v147 offset:4096
	ds_read_b128 v[76:79], v148 offset:4096
	ds_read_b128 v[80:83], v149 offset:4096
	ds_read_b128 v[84:87], v146 offset:8192
	ds_read_b128 v[88:91], v147 offset:8192
	ds_read_b128 v[92:95], v148 offset:8192
	ds_read_b128 v[96:99], v149 offset:8192
	ds_read_b128 v[100:103], v146 offset:12288
	ds_read_b128 v[104:107], v147 offset:12288
	ds_read_b128 v[108:111], v148 offset:12288
	ds_read_b128 v[112:115], v149 offset:12288
	ds_read_b128 v[158:161], v146 offset:16384
	ds_read_b128 v[162:165], v147 offset:16384
	ds_read_b128 v[166:169], v148 offset:16384
	ds_read_b128 v[170:173], v149 offset:16384
	ds_read_b128 v[174:177], v146 offset:20480
	ds_read_b128 v[178:181], v147 offset:20480
	ds_read_b128 v[182:185], v148 offset:20480
	ds_read_b128 v[186:189], v149 offset:20480
	ds_read_b128 v[190:193], v146 offset:24576
	ds_read_b128 v[194:197], v147 offset:24576
	ds_read_b128 v[198:201], v148 offset:24576
	ds_read_b128 v[202:205], v149 offset:24576
	ds_read_b128 v[206:209], v146 offset:28672
	ds_read_b128 v[210:213], v147 offset:28672
	ds_read_b128 v[214:217], v148 offset:28672
	ds_read_b128 v[218:221], v149 offset:28672
	s_waitcnt lgkmcnt(0)
	s_barrier
	s_add_u32 s88, s67, 0x10000
	s_mov_b32 m0, s88
	v_lshl_add_u64 v[4:5], s[78:79], 0, v[18:19]
	global_load_lds_dwordx4 v[4:5], off
	s_add_u32 s78, s78, 0x2000
	s_addc_u32 s79, s79, 0
	s_add_u32 s88, s88, 0x2000
	s_mov_b32 m0, s88
	v_lshl_add_u64 v[4:5], s[78:79], 0, v[18:19]
	global_load_lds_dwordx4 v[4:5], off
	s_add_u32 s78, s78, 0x2000
	s_addc_u32 s79, s79, 0
	s_add_u32 s88, s88, 0x2000
	s_mov_b32 m0, s88
	v_lshl_add_u64 v[4:5], s[78:79], 0, v[18:19]
	global_load_lds_dwordx4 v[4:5], off
	s_add_u32 s78, s78, 0x2000
	s_addc_u32 s79, s79, 0
	s_add_u32 s88, s88, 0x2000
	s_mov_b32 m0, s88
	v_lshl_add_u64 v[4:5], s[78:79], 0, v[18:19]
	global_load_lds_dwordx4 v[4:5], off
	s_add_u32 s78, s78, 0x2000
	s_addc_u32 s79, s79, 0
	s_add_u32 s88, s88, 0x2000
	s_mov_b32 m0, s88
	v_lshl_add_u64 v[4:5], s[78:79], 0, v[18:19]
	global_load_lds_dwordx4 v[4:5], off
	s_add_u32 s78, s78, 0x2000
	s_addc_u32 s79, s79, 0
	s_add_u32 s88, s88, 0x2000
	s_mov_b32 m0, s88
	v_lshl_add_u64 v[4:5], s[78:79], 0, v[18:19]
	global_load_lds_dwordx4 v[4:5], off
	s_add_u32 s78, s78, 0x2000
	s_addc_u32 s79, s79, 0
	s_add_u32 s88, s88, 0x2000
	s_mov_b32 m0, s88
	v_lshl_add_u64 v[4:5], s[78:79], 0, v[18:19]
	global_load_lds_dwordx4 v[4:5], off
	s_add_u32 s78, s78, 0x2000
	s_addc_u32 s79, s79, 0
	s_add_u32 s88, s88, 0x2000
	s_mov_b32 m0, s88
	v_lshl_add_u64 v[4:5], s[78:79], 0, v[18:19]
	global_load_lds_dwordx4 v[4:5], off
	v_mfma_f32_16x16x32_bf16 v[222:225], v[52:55], v[20:23], 0
	v_mfma_f32_16x16x32_bf16 v[222:225], v[56:59], v[24:27], v[222:225]
	v_mfma_f32_16x16x32_bf16 v[222:225], v[60:63], v[28:31], v[222:225]
	v_mfma_f32_16x16x32_bf16 v[222:225], v[64:67], v[32:35], v[222:225]
	v_mfma_f32_16x16x32_bf16 v[226:229], v[68:71], v[20:23], 0
	v_mfma_f32_16x16x32_bf16 v[226:229], v[72:75], v[24:27], v[226:229]
	v_mfma_f32_16x16x32_bf16 v[226:229], v[76:79], v[28:31], v[226:229]
	v_mfma_f32_16x16x32_bf16 v[226:229], v[80:83], v[32:35], v[226:229]
	v_mfma_f32_16x16x32_bf16 v[230:233], v[84:87], v[20:23], 0
	v_mfma_f32_16x16x32_bf16 v[230:233], v[88:91], v[24:27], v[230:233]
	v_mfma_f32_16x16x32_bf16 v[230:233], v[92:95], v[28:31], v[230:233]
	v_mfma_f32_16x16x32_bf16 v[230:233], v[96:99], v[32:35], v[230:233]
	v_mfma_f32_16x16x32_bf16 v[236:239], v[100:103], v[20:23], 0
	v_mfma_f32_16x16x32_bf16 v[236:239], v[104:107], v[24:27], v[236:239]
	v_mfma_f32_16x16x32_bf16 v[236:239], v[108:111], v[28:31], v[236:239]
	v_mfma_f32_16x16x32_bf16 v[236:239], v[112:115], v[32:35], v[236:239]
	v_mfma_f32_16x16x32_bf16 v[240:243], v[158:161], v[20:23], 0
	v_mfma_f32_16x16x32_bf16 v[240:243], v[162:165], v[24:27], v[240:243]
	v_mfma_f32_16x16x32_bf16 v[240:243], v[166:169], v[28:31], v[240:243]
	v_mfma_f32_16x16x32_bf16 v[240:243], v[170:173], v[32:35], v[240:243]
	v_mfma_f32_16x16x32_bf16 v[244:247], v[174:177], v[20:23], 0
	v_mfma_f32_16x16x32_bf16 v[244:247], v[178:181], v[24:27], v[244:247]
	v_mfma_f32_16x16x32_bf16 v[244:247], v[182:185], v[28:31], v[244:247]
	v_mfma_f32_16x16x32_bf16 v[244:247], v[186:189], v[32:35], v[244:247]
	v_mfma_f32_16x16x32_bf16 v[248:251], v[190:193], v[20:23], 0
	v_mfma_f32_16x16x32_bf16 v[248:251], v[194:197], v[24:27], v[248:251]
	v_mfma_f32_16x16x32_bf16 v[248:251], v[198:201], v[28:31], v[248:251]
	v_mfma_f32_16x16x32_bf16 v[248:251], v[202:205], v[32:35], v[248:251]
	v_mfma_f32_16x16x32_bf16 v[252:255], v[206:209], v[20:23], 0
	v_mfma_f32_16x16x32_bf16 v[252:255], v[210:213], v[24:27], v[252:255]
	v_mfma_f32_16x16x32_bf16 v[252:255], v[214:217], v[28:31], v[252:255]
	v_mfma_f32_16x16x32_bf16 v[252:255], v[218:221], v[32:35], v[252:255]
	v_add_f32_e32 v4, 0x00000000, v125
	v_mul_f32_e32 v4, v4, v16
	v_exp_f32_e32 v4, v4
	s_nop 4
	v_cmp_le_f32_e32 vcc, 0x00000000, v125
	v_add_f32_e32 v5, 0xbf800000, v125
	v_mul_f32_e32 v5, v5, v16
	v_cndmask_b32_e32 v222, 0, v222, vcc
	v_exp_f32_e32 v5, v5
	v_mul_f32_e32 v222, v222, v4
	v_cmp_le_f32_e32 vcc, 0x3f800000, v125
	v_add_f32_e32 v4, 0xc0000000, v125
	v_mul_f32_e32 v4, v4, v16
	v_cndmask_b32_e32 v223, 0, v223, vcc
	v_exp_f32_e32 v4, v4
	v_mul_f32_e32 v223, v223, v5
	v_cmp_le_f32_e32 vcc, 0x40000000, v125
	v_add_f32_e32 v5, 0xc0400000, v125
	v_mul_f32_e32 v5, v5, v16
	v_cndmask_b32_e32 v224, 0, v224, vcc
	v_exp_f32_e32 v5, v5
	v_mul_f32_e32 v224, v224, v4
	v_cmp_le_f32_e32 vcc, 0x40400000, v125
	v_add_f32_e32 v4, 0xc1800000, v125
	v_mul_f32_e32 v4, v4, v16
	v_cndmask_b32_e32 v225, 0, v225, vcc
	v_exp_f32_e32 v4, v4
	v_mul_f32_e32 v225, v225, v5
	v_cmp_le_f32_e32 vcc, 0x41800000, v125
	v_add_f32_e32 v5, 0xc1880000, v125
	v_mul_f32_e32 v5, v5, v16
	v_cndmask_b32_e32 v226, 0, v226, vcc
	v_exp_f32_e32 v5, v5
	v_mul_f32_e32 v226, v226, v4
	v_cmp_le_f32_e32 vcc, 0x41880000, v125
	v_add_f32_e32 v4, 0xc1900000, v125
	v_mul_f32_e32 v4, v4, v16
	v_cndmask_b32_e32 v227, 0, v227, vcc
	v_exp_f32_e32 v4, v4
	v_mul_f32_e32 v227, v227, v5
	v_cmp_le_f32_e32 vcc, 0x41900000, v125
	v_add_f32_e32 v5, 0xc1980000, v125
	v_mul_f32_e32 v5, v5, v16
	v_cndmask_b32_e32 v228, 0, v228, vcc
	v_exp_f32_e32 v5, v5
	v_mul_f32_e32 v228, v228, v4
	v_cmp_le_f32_e32 vcc, 0x41980000, v125
	v_add_f32_e32 v4, 0xc2000000, v125
	v_mul_f32_e32 v4, v4, v16
	v_cndmask_b32_e32 v229, 0, v229, vcc
	v_exp_f32_e32 v4, v4
	v_mul_f32_e32 v229, v229, v5
	v_cmp_le_f32_e32 vcc, 0x42000000, v125
	v_add_f32_e32 v5, 0xc2040000, v125
	v_mul_f32_e32 v5, v5, v16
	v_cndmask_b32_e32 v230, 0, v230, vcc
	v_exp_f32_e32 v5, v5
	v_mul_f32_e32 v230, v230, v4
	v_cmp_le_f32_e32 vcc, 0x42040000, v125
	v_add_f32_e32 v4, 0xc2080000, v125
	v_mul_f32_e32 v4, v4, v16
	v_cndmask_b32_e32 v231, 0, v231, vcc
	v_exp_f32_e32 v4, v4
	v_mul_f32_e32 v231, v231, v5
	v_cmp_le_f32_e32 vcc, 0x42080000, v125
	v_add_f32_e32 v5, 0xc20c0000, v125
	v_mul_f32_e32 v5, v5, v16
	v_cndmask_b32_e32 v232, 0, v232, vcc
	v_exp_f32_e32 v5, v5
	v_mul_f32_e32 v232, v232, v4
	v_cmp_le_f32_e32 vcc, 0x420c0000, v125
	v_add_f32_e32 v4, 0xc2400000, v125
	v_mul_f32_e32 v4, v4, v16
	v_cndmask_b32_e32 v233, 0, v233, vcc
	v_exp_f32_e32 v4, v4
	v_mul_f32_e32 v233, v233, v5
	v_cmp_le_f32_e32 vcc, 0x42400000, v125
	v_add_f32_e32 v5, 0xc2440000, v125
	v_mul_f32_e32 v5, v5, v16
	v_cndmask_b32_e32 v236, 0, v236, vcc
	v_exp_f32_e32 v5, v5
	v_mul_f32_e32 v236, v236, v4
	v_cmp_le_f32_e32 vcc, 0x42440000, v125
	v_add_f32_e32 v4, 0xc2480000, v125
	v_mul_f32_e32 v4, v4, v16
	v_cndmask_b32_e32 v237, 0, v237, vcc
	v_exp_f32_e32 v4, v4
	v_mul_f32_e32 v237, v237, v5
	v_cmp_le_f32_e32 vcc, 0x42480000, v125
	v_add_f32_e32 v5, 0xc24c0000, v125
	v_mul_f32_e32 v5, v5, v16
	v_cndmask_b32_e32 v238, 0, v238, vcc
	v_exp_f32_e32 v5, v5
	v_mul_f32_e32 v238, v238, v4
	v_cmp_le_f32_e32 vcc, 0x424c0000, v125
	v_add_f32_e32 v4, 0xc2800000, v125
	v_mul_f32_e32 v4, v4, v16
	v_cndmask_b32_e32 v239, 0, v239, vcc
	v_exp_f32_e32 v4, v4
	v_mul_f32_e32 v239, v239, v5
	v_cmp_le_f32_e32 vcc, 0x42800000, v125
	v_add_f32_e32 v5, 0xc2820000, v125
	v_mul_f32_e32 v5, v5, v16
	v_cndmask_b32_e32 v240, 0, v240, vcc
	v_exp_f32_e32 v5, v5
	v_mul_f32_e32 v240, v240, v4
	v_cmp_le_f32_e32 vcc, 0x42820000, v125
	v_add_f32_e32 v4, 0xc2840000, v125
	v_mul_f32_e32 v4, v4, v16
	v_cndmask_b32_e32 v241, 0, v241, vcc
	v_exp_f32_e32 v4, v4
	v_mul_f32_e32 v241, v241, v5
	v_cmp_le_f32_e32 vcc, 0x42840000, v125
	v_add_f32_e32 v5, 0xc2860000, v125
	v_mul_f32_e32 v5, v5, v16
	v_cndmask_b32_e32 v242, 0, v242, vcc
	v_exp_f32_e32 v5, v5
	v_mul_f32_e32 v242, v242, v4
	v_cmp_le_f32_e32 vcc, 0x42860000, v125
	v_add_f32_e32 v4, 0xc2a00000, v125
	v_mul_f32_e32 v4, v4, v16
	v_cndmask_b32_e32 v243, 0, v243, vcc
	v_exp_f32_e32 v4, v4
	v_mul_f32_e32 v243, v243, v5
	v_cmp_le_f32_e32 vcc, 0x42a00000, v125
	v_add_f32_e32 v5, 0xc2a20000, v125
	v_mul_f32_e32 v5, v5, v16
	v_cndmask_b32_e32 v244, 0, v244, vcc
	v_exp_f32_e32 v5, v5
	v_mul_f32_e32 v244, v244, v4
	v_cmp_le_f32_e32 vcc, 0x42a20000, v125
	v_add_f32_e32 v4, 0xc2a40000, v125
	v_mul_f32_e32 v4, v4, v16
	v_cndmask_b32_e32 v245, 0, v245, vcc
	v_exp_f32_e32 v4, v4
	v_mul_f32_e32 v245, v245, v5
	v_cmp_le_f32_e32 vcc, 0x42a40000, v125
	v_add_f32_e32 v5, 0xc2a60000, v125
	v_mul_f32_e32 v5, v5, v16
	v_cndmask_b32_e32 v246, 0, v246, vcc
	v_exp_f32_e32 v5, v5
	v_mul_f32_e32 v246, v246, v4
	v_cmp_le_f32_e32 vcc, 0x42a60000, v125
	v_add_f32_e32 v4, 0xc2c00000, v125
	v_mul_f32_e32 v4, v4, v16
	v_cndmask_b32_e32 v247, 0, v247, vcc
	v_exp_f32_e32 v4, v4
	v_mul_f32_e32 v247, v247, v5
	v_cmp_le_f32_e32 vcc, 0x42c00000, v125
	v_add_f32_e32 v5, 0xc2c20000, v125
	v_mul_f32_e32 v5, v5, v16
	v_cndmask_b32_e32 v248, 0, v248, vcc
	v_exp_f32_e32 v5, v5
	v_mul_f32_e32 v248, v248, v4
	v_cmp_le_f32_e32 vcc, 0x42c20000, v125
	v_add_f32_e32 v4, 0xc2c40000, v125
	v_mul_f32_e32 v4, v4, v16
	v_cndmask_b32_e32 v249, 0, v249, vcc
	v_exp_f32_e32 v4, v4
	v_mul_f32_e32 v249, v249, v5
	v_cmp_le_f32_e32 vcc, 0x42c40000, v125
	v_add_f32_e32 v5, 0xc2c60000, v125
	v_mul_f32_e32 v5, v5, v16
	v_cndmask_b32_e32 v250, 0, v250, vcc
	v_exp_f32_e32 v5, v5
	v_mul_f32_e32 v250, v250, v4
	v_cmp_le_f32_e32 vcc, 0x42c60000, v125
	v_add_f32_e32 v4, 0xc2e00000, v125
	v_mul_f32_e32 v4, v4, v16
	v_cndmask_b32_e32 v251, 0, v251, vcc
	v_exp_f32_e32 v4, v4
	v_mul_f32_e32 v251, v251, v5
	v_cmp_le_f32_e32 vcc, 0x42e00000, v125
	v_add_f32_e32 v5, 0xc2e20000, v125
	v_mul_f32_e32 v5, v5, v16
	v_cndmask_b32_e32 v252, 0, v252, vcc
	v_exp_f32_e32 v5, v5
	v_mul_f32_e32 v252, v252, v4
	v_cmp_le_f32_e32 vcc, 0x42e20000, v125
	v_add_f32_e32 v4, 0xc2e40000, v125
	v_mul_f32_e32 v4, v4, v16
	v_cndmask_b32_e32 v253, 0, v253, vcc
	v_exp_f32_e32 v4, v4
	v_mul_f32_e32 v253, v253, v5
	v_cmp_le_f32_e32 vcc, 0x42e40000, v125
	v_add_f32_e32 v5, 0xc2e60000, v125
	v_mul_f32_e32 v5, v5, v16
	v_cndmask_b32_e32 v254, 0, v254, vcc
	v_exp_f32_e32 v5, v5
	v_mul_f32_e32 v254, v254, v4
	v_cmp_le_f32_e32 vcc, 0x42e60000, v125
	s_nop 1
	v_cndmask_b32_e32 v255, 0, v255, vcc
	v_mul_f32_e32 v255, v255, v5
	v_cvt_pk_bf16_f32 v36, v222, v223
	v_cvt_pk_bf16_f32 v37, v224, v225
	v_cvt_pk_bf16_f32 v38, v226, v227
	v_cvt_pk_bf16_f32 v39, v228, v229
	v_cvt_pk_bf16_f32 v40, v230, v231
	v_cvt_pk_bf16_f32 v41, v232, v233
	v_cvt_pk_bf16_f32 v42, v236, v237
	v_cvt_pk_bf16_f32 v43, v238, v239
	v_cvt_pk_bf16_f32 v44, v240, v241
	v_cvt_pk_bf16_f32 v45, v242, v243
	v_cvt_pk_bf16_f32 v46, v244, v245
	v_cvt_pk_bf16_f32 v47, v246, v247
	v_cvt_pk_bf16_f32 v48, v248, v249
	v_cvt_pk_bf16_f32 v49, v250, v251
	v_cvt_pk_bf16_f32 v50, v252, v253
	v_cvt_pk_bf16_f32 v51, v254, v255
	global_load_dwordx2 v[222:223], v140, s[72:73] offset:0
	global_load_dwordx2 v[224:225], v140, s[72:73] offset:32
	global_load_dwordx2 v[226:227], v140, s[72:73] offset:64
	global_load_dwordx2 v[228:229], v140, s[72:73] offset:96
	global_load_dwordx2 v[230:231], v140, s[72:73] offset:128
	global_load_dwordx2 v[232:233], v140, s[72:73] offset:160
	global_load_dwordx2 v[236:237], v140, s[72:73] offset:192
	global_load_dwordx2 v[238:239], v140, s[72:73] offset:224
	global_load_dwordx2 v[240:241], v140, s[72:73] offset:256
	global_load_dwordx2 v[242:243], v140, s[72:73] offset:288
	global_load_dwordx2 v[244:245], v140, s[72:73] offset:320
	global_load_dwordx2 v[246:247], v140, s[72:73] offset:352
	global_load_dwordx2 v[248:249], v140, s[72:73] offset:384
	global_load_dwordx2 v[250:251], v140, s[72:73] offset:416
	global_load_dwordx2 v[252:253], v140, s[72:73] offset:448
	global_load_dwordx2 v[254:255], v140, s[72:73] offset:480
	s_waitcnt vmcnt(16)
	s_barrier
	ds_read_b128 v[158:161], v142 offset:0
	ds_read_b128 v[162:165], v143 offset:0
	ds_read_b128 v[166:169], v144 offset:0
	ds_read_b128 v[170:173], v145 offset:0
	ds_read_b64 v[174:175], v150 offset:0
	ds_read_b64 v[176:177], v154 offset:0
	ds_read_b64 v[178:179], v151 offset:0
	ds_read_b64 v[180:181], v155 offset:0
	ds_read_b64 v[182:183], v152 offset:0
	ds_read_b64 v[184:185], v156 offset:0
	ds_read_b64 v[186:187], v153 offset:0
	ds_read_b64 v[188:189], v157 offset:0
	ds_read_b128 v[190:193], v142 offset:4096
	ds_read_b128 v[194:197], v143 offset:4096
	ds_read_b128 v[198:201], v144 offset:4096
	ds_read_b128 v[202:205], v145 offset:4096
	ds_read_b64 v[206:207], v150 offset:4096
	ds_read_b64 v[208:209], v154 offset:4096
	ds_read_b64 v[210:211], v151 offset:4096
	ds_read_b64 v[212:213], v155 offset:4096
	ds_read_b64 v[214:215], v152 offset:4096
	ds_read_b64 v[216:217], v156 offset:4096
	ds_read_b64 v[218:219], v153 offset:4096
	ds_read_b64 v[220:221], v157 offset:4096
	s_waitcnt lgkmcnt(12)
	v_mfma_f32_16x16x32_bf16 v[116:119], v[158:161], v[20:23], 0
	v_mfma_f32_16x16x32_bf16 v[116:119], v[162:165], v[24:27], v[116:119]
	v_mfma_f32_16x16x32_bf16 v[116:119], v[166:169], v[28:31], v[116:119]
	v_mfma_f32_16x16x32_bf16 v[116:119], v[170:173], v[32:35], v[116:119]
	v_mfma_f32_16x16x32_bf16 v[120:123], v[174:177], v[36:39], 0
	v_mfma_f32_16x16x32_bf16 v[120:123], v[178:181], v[40:43], v[120:123]
	v_mfma_f32_16x16x32_bf16 v[120:123], v[182:185], v[44:47], v[120:123]
	v_mfma_f32_16x16x32_bf16 v[120:123], v[186:189], v[48:51], v[120:123]
	ds_read_b128 v[158:161], v142 offset:8192
	ds_read_b128 v[162:165], v143 offset:8192
	ds_read_b128 v[166:169], v144 offset:8192
	ds_read_b128 v[170:173], v145 offset:8192
	ds_read_b64 v[174:175], v150 offset:8192
	ds_read_b64 v[176:177], v154 offset:8192
	ds_read_b64 v[178:179], v151 offset:8192
	ds_read_b64 v[180:181], v155 offset:8192
	ds_read_b64 v[182:183], v152 offset:8192
	ds_read_b64 v[184:185], v156 offset:8192
	ds_read_b64 v[186:187], v153 offset:8192
	ds_read_b64 v[188:189], v157 offset:8192
	s_waitcnt lgkmcnt(12)
	v_mfma_f32_16x16x32_bf16 v[130:133], v[190:193], v[20:23], 0
	v_mfma_f32_16x16x32_bf16 v[130:133], v[194:197], v[24:27], v[130:133]
	v_mfma_f32_16x16x32_bf16 v[130:133], v[198:201], v[28:31], v[130:133]
	v_mfma_f32_16x16x32_bf16 v[130:133], v[202:205], v[32:35], v[130:133]
	v_mfma_f32_16x16x32_bf16 v[134:137], v[206:209], v[36:39], 0
	v_mfma_f32_16x16x32_bf16 v[134:137], v[210:213], v[40:43], v[134:137]
	v_mfma_f32_16x16x32_bf16 v[134:137], v[214:217], v[44:47], v[134:137]
	v_mfma_f32_16x16x32_bf16 v[134:137], v[218:221], v[48:51], v[134:137]
	v_fma_f32 v52, v116, v126, v120
	v_fma_f32 v53, v117, v126, v121
	v_fma_f32 v54, v118, v126, v122
	v_fma_f32 v55, v119, v126, v123
	ds_read_b128 v[190:193], v142 offset:12288
	ds_read_b128 v[194:197], v143 offset:12288
	ds_read_b128 v[198:201], v144 offset:12288
	ds_read_b128 v[202:205], v145 offset:12288
	ds_read_b64 v[206:207], v150 offset:12288
	ds_read_b64 v[208:209], v154 offset:12288
	ds_read_b64 v[210:211], v151 offset:12288
	ds_read_b64 v[212:213], v155 offset:12288
	ds_read_b64 v[214:215], v152 offset:12288
	ds_read_b64 v[216:217], v156 offset:12288
	ds_read_b64 v[218:219], v153 offset:12288
	ds_read_b64 v[220:221], v157 offset:12288
	s_waitcnt lgkmcnt(12)
	v_mfma_f32_16x16x32_bf16 v[116:119], v[158:161], v[20:23], 0
	v_mfma_f32_16x16x32_bf16 v[116:119], v[162:165], v[24:27], v[116:119]
	v_mfma_f32_16x16x32_bf16 v[116:119], v[166:169], v[28:31], v[116:119]
	v_mfma_f32_16x16x32_bf16 v[116:119], v[170:173], v[32:35], v[116:119]
	v_mfma_f32_16x16x32_bf16 v[120:123], v[174:177], v[36:39], 0
	v_mfma_f32_16x16x32_bf16 v[120:123], v[178:181], v[40:43], v[120:123]
	v_mfma_f32_16x16x32_bf16 v[120:123], v[182:185], v[44:47], v[120:123]
	v_mfma_f32_16x16x32_bf16 v[120:123], v[186:189], v[48:51], v[120:123]
	v_fma_f32 v56, v130, v126, v134
	v_fma_f32 v57, v131, v126, v135
	v_fma_f32 v58, v132, v126, v136
	v_fma_f32 v59, v133, v126, v137
	ds_read_b128 v[158:161], v142 offset:16384
	ds_read_b128 v[162:165], v143 offset:16384
	ds_read_b128 v[166:169], v144 offset:16384
	ds_read_b128 v[170:173], v145 offset:16384
	ds_read_b64 v[174:175], v150 offset:16384
	ds_read_b64 v[176:177], v154 offset:16384
	ds_read_b64 v[178:179], v151 offset:16384
	ds_read_b64 v[180:181], v155 offset:16384
	ds_read_b64 v[182:183], v152 offset:16384
	ds_read_b64 v[184:185], v156 offset:16384
	ds_read_b64 v[186:187], v153 offset:16384
	ds_read_b64 v[188:189], v157 offset:16384
	s_waitcnt lgkmcnt(12)
	v_mfma_f32_16x16x32_bf16 v[130:133], v[190:193], v[20:23], 0
	v_mfma_f32_16x16x32_bf16 v[130:133], v[194:197], v[24:27], v[130:133]
	v_mfma_f32_16x16x32_bf16 v[130:133], v[198:201], v[28:31], v[130:133]
	v_mfma_f32_16x16x32_bf16 v[130:133], v[202:205], v[32:35], v[130:133]
	v_mfma_f32_16x16x32_bf16 v[134:137], v[206:209], v[36:39], 0
	v_mfma_f32_16x16x32_bf16 v[134:137], v[210:213], v[40:43], v[134:137]
	v_mfma_f32_16x16x32_bf16 v[134:137], v[214:217], v[44:47], v[134:137]
	v_mfma_f32_16x16x32_bf16 v[134:137], v[218:221], v[48:51], v[134:137]
	v_fma_f32 v60, v116, v126, v120
	v_fma_f32 v61, v117, v126, v121
	v_fma_f32 v62, v118, v126, v122
	v_fma_f32 v63, v119, v126, v123
	ds_read_b128 v[190:193], v142 offset:20480
	ds_read_b128 v[194:197], v143 offset:20480
	ds_read_b128 v[198:201], v144 offset:20480
	ds_read_b128 v[202:205], v145 offset:20480
	ds_read_b64 v[206:207], v150 offset:20480
	ds_read_b64 v[208:209], v154 offset:20480
	ds_read_b64 v[210:211], v151 offset:20480
	ds_read_b64 v[212:213], v155 offset:20480
	ds_read_b64 v[214:215], v152 offset:20480
	ds_read_b64 v[216:217], v156 offset:20480
	ds_read_b64 v[218:219], v153 offset:20480
	ds_read_b64 v[220:221], v157 offset:20480
	s_waitcnt lgkmcnt(12)
	v_mfma_f32_16x16x32_bf16 v[116:119], v[158:161], v[20:23], 0
	v_mfma_f32_16x16x32_bf16 v[116:119], v[162:165], v[24:27], v[116:119]
	v_mfma_f32_16x16x32_bf16 v[116:119], v[166:169], v[28:31], v[116:119]
	v_mfma_f32_16x16x32_bf16 v[116:119], v[170:173], v[32:35], v[116:119]
	v_mfma_f32_16x16x32_bf16 v[120:123], v[174:177], v[36:39], 0
	v_mfma_f32_16x16x32_bf16 v[120:123], v[178:181], v[40:43], v[120:123]
	v_mfma_f32_16x16x32_bf16 v[120:123], v[182:185], v[44:47], v[120:123]
	v_mfma_f32_16x16x32_bf16 v[120:123], v[186:189], v[48:51], v[120:123]
	v_fma_f32 v64, v130, v126, v134
	v_fma_f32 v65, v131, v126, v135
	v_fma_f32 v66, v132, v126, v136
	v_fma_f32 v67, v133, v126, v137
	ds_read_b128 v[158:161], v142 offset:24576
	ds_read_b128 v[162:165], v143 offset:24576
	ds_read_b128 v[166:169], v144 offset:24576
	ds_read_b128 v[170:173], v145 offset:24576
	ds_read_b64 v[174:175], v150 offset:24576
	ds_read_b64 v[176:177], v154 offset:24576
	ds_read_b64 v[178:179], v151 offset:24576
	ds_read_b64 v[180:181], v155 offset:24576
	ds_read_b64 v[182:183], v152 offset:24576
	ds_read_b64 v[184:185], v156 offset:24576
	ds_read_b64 v[186:187], v153 offset:24576
	ds_read_b64 v[188:189], v157 offset:24576
	s_waitcnt lgkmcnt(12)
	v_mfma_f32_16x16x32_bf16 v[130:133], v[190:193], v[20:23], 0
	v_mfma_f32_16x16x32_bf16 v[130:133], v[194:197], v[24:27], v[130:133]
	v_mfma_f32_16x16x32_bf16 v[130:133], v[198:201], v[28:31], v[130:133]
	v_mfma_f32_16x16x32_bf16 v[130:133], v[202:205], v[32:35], v[130:133]
	v_mfma_f32_16x16x32_bf16 v[134:137], v[206:209], v[36:39], 0
	v_mfma_f32_16x16x32_bf16 v[134:137], v[210:213], v[40:43], v[134:137]
	v_mfma_f32_16x16x32_bf16 v[134:137], v[214:217], v[44:47], v[134:137]
	v_mfma_f32_16x16x32_bf16 v[134:137], v[218:221], v[48:51], v[134:137]
	v_fma_f32 v68, v116, v126, v120
	v_fma_f32 v69, v117, v126, v121
	v_fma_f32 v70, v118, v126, v122
	v_fma_f32 v71, v119, v126, v123
	ds_read_b128 v[190:193], v142 offset:28672
	ds_read_b128 v[194:197], v143 offset:28672
	ds_read_b128 v[198:201], v144 offset:28672
	ds_read_b128 v[202:205], v145 offset:28672
	ds_read_b64 v[206:207], v150 offset:28672
	ds_read_b64 v[208:209], v154 offset:28672
	ds_read_b64 v[210:211], v151 offset:28672
	ds_read_b64 v[212:213], v155 offset:28672
	ds_read_b64 v[214:215], v152 offset:28672
	ds_read_b64 v[216:217], v156 offset:28672
	ds_read_b64 v[218:219], v153 offset:28672
	ds_read_b64 v[220:221], v157 offset:28672
	s_waitcnt lgkmcnt(12)
	v_mfma_f32_16x16x32_bf16 v[116:119], v[158:161], v[20:23], 0
	v_mfma_f32_16x16x32_bf16 v[116:119], v[162:165], v[24:27], v[116:119]
	v_mfma_f32_16x16x32_bf16 v[116:119], v[166:169], v[28:31], v[116:119]
	v_mfma_f32_16x16x32_bf16 v[116:119], v[170:173], v[32:35], v[116:119]
	v_mfma_f32_16x16x32_bf16 v[120:123], v[174:177], v[36:39], 0
	v_mfma_f32_16x16x32_bf16 v[120:123], v[178:181], v[40:43], v[120:123]
	v_mfma_f32_16x16x32_bf16 v[120:123], v[182:185], v[44:47], v[120:123]
	v_mfma_f32_16x16x32_bf16 v[120:123], v[186:189], v[48:51], v[120:123]
	v_fma_f32 v72, v130, v126, v134
	v_fma_f32 v73, v131, v126, v135
	v_fma_f32 v74, v132, v126, v136
	v_fma_f32 v75, v133, v126, v137
	ds_read_b128 v[158:161], v142 offset:32768
	ds_read_b128 v[162:165], v143 offset:32768
	ds_read_b128 v[166:169], v144 offset:32768
	ds_read_b128 v[170:173], v145 offset:32768
	ds_read_b64 v[174:175], v150 offset:32768
	ds_read_b64 v[176:177], v154 offset:32768
	ds_read_b64 v[178:179], v151 offset:32768
	ds_read_b64 v[180:181], v155 offset:32768
	ds_read_b64 v[182:183], v152 offset:32768
	ds_read_b64 v[184:185], v156 offset:32768
	ds_read_b64 v[186:187], v153 offset:32768
	ds_read_b64 v[188:189], v157 offset:32768
	s_waitcnt lgkmcnt(12)
	v_mfma_f32_16x16x32_bf16 v[130:133], v[190:193], v[20:23], 0
	v_mfma_f32_16x16x32_bf16 v[130:133], v[194:197], v[24:27], v[130:133]
	v_mfma_f32_16x16x32_bf16 v[130:133], v[198:201], v[28:31], v[130:133]
	v_mfma_f32_16x16x32_bf16 v[130:133], v[202:205], v[32:35], v[130:133]
	v_mfma_f32_16x16x32_bf16 v[134:137], v[206:209], v[36:39], 0
	v_mfma_f32_16x16x32_bf16 v[134:137], v[210:213], v[40:43], v[134:137]
	v_mfma_f32_16x16x32_bf16 v[134:137], v[214:217], v[44:47], v[134:137]
	v_mfma_f32_16x16x32_bf16 v[134:137], v[218:221], v[48:51], v[134:137]
	v_fma_f32 v76, v116, v126, v120
	v_fma_f32 v77, v117, v126, v121
	v_fma_f32 v78, v118, v126, v122
	v_fma_f32 v79, v119, v126, v123
	ds_read_b128 v[190:193], v142 offset:36864
	ds_read_b128 v[194:197], v143 offset:36864
	ds_read_b128 v[198:201], v144 offset:36864
	ds_read_b128 v[202:205], v145 offset:36864
	ds_read_b64 v[206:207], v150 offset:36864
	ds_read_b64 v[208:209], v154 offset:36864
	ds_read_b64 v[210:211], v151 offset:36864
	ds_read_b64 v[212:213], v155 offset:36864
	ds_read_b64 v[214:215], v152 offset:36864
	ds_read_b64 v[216:217], v156 offset:36864
	ds_read_b64 v[218:219], v153 offset:36864
	ds_read_b64 v[220:221], v157 offset:36864
	s_waitcnt lgkmcnt(12)
	v_mfma_f32_16x16x32_bf16 v[116:119], v[158:161], v[20:23], 0
	v_mfma_f32_16x16x32_bf16 v[116:119], v[162:165], v[24:27], v[116:119]
	v_mfma_f32_16x16x32_bf16 v[116:119], v[166:169], v[28:31], v[116:119]
	v_mfma_f32_16x16x32_bf16 v[116:119], v[170:173], v[32:35], v[116:119]
	v_mfma_f32_16x16x32_bf16 v[120:123], v[174:177], v[36:39], 0
	v_mfma_f32_16x16x32_bf16 v[120:123], v[178:181], v[40:43], v[120:123]
	v_mfma_f32_16x16x32_bf16 v[120:123], v[182:185], v[44:47], v[120:123]
	v_mfma_f32_16x16x32_bf16 v[120:123], v[186:189], v[48:51], v[120:123]
	v_fma_f32 v80, v130, v126, v134
	v_fma_f32 v81, v131, v126, v135
	v_fma_f32 v82, v132, v126, v136
	v_fma_f32 v83, v133, v126, v137
	ds_read_b128 v[158:161], v142 offset:40960
	ds_read_b128 v[162:165], v143 offset:40960
	ds_read_b128 v[166:169], v144 offset:40960
	ds_read_b128 v[170:173], v145 offset:40960
	ds_read_b64 v[174:175], v150 offset:40960
	ds_read_b64 v[176:177], v154 offset:40960
	ds_read_b64 v[178:179], v151 offset:40960
	ds_read_b64 v[180:181], v155 offset:40960
	ds_read_b64 v[182:183], v152 offset:40960
	ds_read_b64 v[184:185], v156 offset:40960
	ds_read_b64 v[186:187], v153 offset:40960
	ds_read_b64 v[188:189], v157 offset:40960
	s_waitcnt lgkmcnt(12)
	v_mfma_f32_16x16x32_bf16 v[130:133], v[190:193], v[20:23], 0
	v_mfma_f32_16x16x32_bf16 v[130:133], v[194:197], v[24:27], v[130:133]
	v_mfma_f32_16x16x32_bf16 v[130:133], v[198:201], v[28:31], v[130:133]
	v_mfma_f32_16x16x32_bf16 v[130:133], v[202:205], v[32:35], v[130:133]
	v_mfma_f32_16x16x32_bf16 v[134:137], v[206:209], v[36:39], 0
	v_mfma_f32_16x16x32_bf16 v[134:137], v[210:213], v[40:43], v[134:137]
	v_mfma_f32_16x16x32_bf16 v[134:137], v[214:217], v[44:47], v[134:137]
	v_mfma_f32_16x16x32_bf16 v[134:137], v[218:221], v[48:51], v[134:137]
	v_fma_f32 v84, v116, v126, v120
	v_fma_f32 v85, v117, v126, v121
	v_fma_f32 v86, v118, v126, v122
	v_fma_f32 v87, v119, v126, v123
	ds_read_b128 v[190:193], v142 offset:45056
	ds_read_b128 v[194:197], v143 offset:45056
	ds_read_b128 v[198:201], v144 offset:45056
	ds_read_b128 v[202:205], v145 offset:45056
	ds_read_b64 v[206:207], v150 offset:45056
	ds_read_b64 v[208:209], v154 offset:45056
	ds_read_b64 v[210:211], v151 offset:45056
	ds_read_b64 v[212:213], v155 offset:45056
	ds_read_b64 v[214:215], v152 offset:45056
	ds_read_b64 v[216:217], v156 offset:45056
	ds_read_b64 v[218:219], v153 offset:45056
	ds_read_b64 v[220:221], v157 offset:45056
	s_waitcnt lgkmcnt(12)
	v_mfma_f32_16x16x32_bf16 v[116:119], v[158:161], v[20:23], 0
	v_mfma_f32_16x16x32_bf16 v[116:119], v[162:165], v[24:27], v[116:119]
	v_mfma_f32_16x16x32_bf16 v[116:119], v[166:169], v[28:31], v[116:119]
	v_mfma_f32_16x16x32_bf16 v[116:119], v[170:173], v[32:35], v[116:119]
	v_mfma_f32_16x16x32_bf16 v[120:123], v[174:177], v[36:39], 0
	v_mfma_f32_16x16x32_bf16 v[120:123], v[178:181], v[40:43], v[120:123]
	v_mfma_f32_16x16x32_bf16 v[120:123], v[182:185], v[44:47], v[120:123]
	v_mfma_f32_16x16x32_bf16 v[120:123], v[186:189], v[48:51], v[120:123]
	v_fma_f32 v88, v130, v126, v134
	v_fma_f32 v89, v131, v126, v135
	v_fma_f32 v90, v132, v126, v136
	v_fma_f32 v91, v133, v126, v137
	ds_read_b128 v[158:161], v142 offset:49152
	ds_read_b128 v[162:165], v143 offset:49152
	ds_read_b128 v[166:169], v144 offset:49152
	ds_read_b128 v[170:173], v145 offset:49152
	ds_read_b64 v[174:175], v150 offset:49152
	ds_read_b64 v[176:177], v154 offset:49152
	ds_read_b64 v[178:179], v151 offset:49152
	ds_read_b64 v[180:181], v155 offset:49152
	ds_read_b64 v[182:183], v152 offset:49152
	ds_read_b64 v[184:185], v156 offset:49152
	ds_read_b64 v[186:187], v153 offset:49152
	ds_read_b64 v[188:189], v157 offset:49152
	s_waitcnt lgkmcnt(12)
	v_mfma_f32_16x16x32_bf16 v[130:133], v[190:193], v[20:23], 0
	v_mfma_f32_16x16x32_bf16 v[130:133], v[194:197], v[24:27], v[130:133]
	v_mfma_f32_16x16x32_bf16 v[130:133], v[198:201], v[28:31], v[130:133]
	v_mfma_f32_16x16x32_bf16 v[130:133], v[202:205], v[32:35], v[130:133]
	v_mfma_f32_16x16x32_bf16 v[134:137], v[206:209], v[36:39], 0
	v_mfma_f32_16x16x32_bf16 v[134:137], v[210:213], v[40:43], v[134:137]
	v_mfma_f32_16x16x32_bf16 v[134:137], v[214:217], v[44:47], v[134:137]
	v_mfma_f32_16x16x32_bf16 v[134:137], v[218:221], v[48:51], v[134:137]
	v_fma_f32 v92, v116, v126, v120
	v_fma_f32 v93, v117, v126, v121
	v_fma_f32 v94, v118, v126, v122
	v_fma_f32 v95, v119, v126, v123
	ds_read_b128 v[190:193], v142 offset:53248
	ds_read_b128 v[194:197], v143 offset:53248
	ds_read_b128 v[198:201], v144 offset:53248
	ds_read_b128 v[202:205], v145 offset:53248
	ds_read_b64 v[206:207], v150 offset:53248
	ds_read_b64 v[208:209], v154 offset:53248
	ds_read_b64 v[210:211], v151 offset:53248
	ds_read_b64 v[212:213], v155 offset:53248
	ds_read_b64 v[214:215], v152 offset:53248
	ds_read_b64 v[216:217], v156 offset:53248
	ds_read_b64 v[218:219], v153 offset:53248
	ds_read_b64 v[220:221], v157 offset:53248
	s_waitcnt lgkmcnt(12)
	v_mfma_f32_16x16x32_bf16 v[116:119], v[158:161], v[20:23], 0
	v_mfma_f32_16x16x32_bf16 v[116:119], v[162:165], v[24:27], v[116:119]
	v_mfma_f32_16x16x32_bf16 v[116:119], v[166:169], v[28:31], v[116:119]
	v_mfma_f32_16x16x32_bf16 v[116:119], v[170:173], v[32:35], v[116:119]
	v_mfma_f32_16x16x32_bf16 v[120:123], v[174:177], v[36:39], 0
	v_mfma_f32_16x16x32_bf16 v[120:123], v[178:181], v[40:43], v[120:123]
	v_mfma_f32_16x16x32_bf16 v[120:123], v[182:185], v[44:47], v[120:123]
	v_mfma_f32_16x16x32_bf16 v[120:123], v[186:189], v[48:51], v[120:123]
	v_fma_f32 v96, v130, v126, v134
	v_fma_f32 v97, v131, v126, v135
	v_fma_f32 v98, v132, v126, v136
	v_fma_f32 v99, v133, v126, v137
	ds_read_b128 v[158:161], v142 offset:57344
	ds_read_b128 v[162:165], v143 offset:57344
	ds_read_b128 v[166:169], v144 offset:57344
	ds_read_b128 v[170:173], v145 offset:57344
	ds_read_b64 v[174:175], v150 offset:57344
	ds_read_b64 v[176:177], v154 offset:57344
	ds_read_b64 v[178:179], v151 offset:57344
	ds_read_b64 v[180:181], v155 offset:57344
	ds_read_b64 v[182:183], v152 offset:57344
	ds_read_b64 v[184:185], v156 offset:57344
	ds_read_b64 v[186:187], v153 offset:57344
	ds_read_b64 v[188:189], v157 offset:57344
	s_waitcnt lgkmcnt(12)
	v_mfma_f32_16x16x32_bf16 v[130:133], v[190:193], v[20:23], 0
	v_mfma_f32_16x16x32_bf16 v[130:133], v[194:197], v[24:27], v[130:133]
	v_mfma_f32_16x16x32_bf16 v[130:133], v[198:201], v[28:31], v[130:133]
	v_mfma_f32_16x16x32_bf16 v[130:133], v[202:205], v[32:35], v[130:133]
	v_mfma_f32_16x16x32_bf16 v[134:137], v[206:209], v[36:39], 0
	v_mfma_f32_16x16x32_bf16 v[134:137], v[210:213], v[40:43], v[134:137]
	v_mfma_f32_16x16x32_bf16 v[134:137], v[214:217], v[44:47], v[134:137]
	v_mfma_f32_16x16x32_bf16 v[134:137], v[218:221], v[48:51], v[134:137]
	v_fma_f32 v100, v116, v126, v120
	v_fma_f32 v101, v117, v126, v121
	v_fma_f32 v102, v118, v126, v122
	v_fma_f32 v103, v119, v126, v123
	ds_read_b128 v[190:193], v142 offset:61440
	ds_read_b128 v[194:197], v143 offset:61440
	ds_read_b128 v[198:201], v144 offset:61440
	ds_read_b128 v[202:205], v145 offset:61440
	ds_read_b64 v[206:207], v150 offset:61440
	ds_read_b64 v[208:209], v154 offset:61440
	ds_read_b64 v[210:211], v151 offset:61440
	ds_read_b64 v[212:213], v155 offset:61440
	ds_read_b64 v[214:215], v152 offset:61440
	ds_read_b64 v[216:217], v156 offset:61440
	ds_read_b64 v[218:219], v153 offset:61440
	ds_read_b64 v[220:221], v157 offset:61440
	s_waitcnt lgkmcnt(12)
	v_mfma_f32_16x16x32_bf16 v[116:119], v[158:161], v[20:23], 0
	v_mfma_f32_16x16x32_bf16 v[116:119], v[162:165], v[24:27], v[116:119]
	v_mfma_f32_16x16x32_bf16 v[116:119], v[166:169], v[28:31], v[116:119]
	v_mfma_f32_16x16x32_bf16 v[116:119], v[170:173], v[32:35], v[116:119]
	v_mfma_f32_16x16x32_bf16 v[120:123], v[174:177], v[36:39], 0
	v_mfma_f32_16x16x32_bf16 v[120:123], v[178:181], v[40:43], v[120:123]
	v_mfma_f32_16x16x32_bf16 v[120:123], v[182:185], v[44:47], v[120:123]
	v_mfma_f32_16x16x32_bf16 v[120:123], v[186:189], v[48:51], v[120:123]
	v_fma_f32 v104, v130, v126, v134
	v_fma_f32 v105, v131, v126, v135
	v_fma_f32 v106, v132, v126, v136
	v_fma_f32 v107, v133, v126, v137
	s_waitcnt lgkmcnt(0)
	v_mfma_f32_16x16x32_bf16 v[130:133], v[190:193], v[20:23], 0
	v_mfma_f32_16x16x32_bf16 v[130:133], v[194:197], v[24:27], v[130:133]
	v_mfma_f32_16x16x32_bf16 v[130:133], v[198:201], v[28:31], v[130:133]
	v_mfma_f32_16x16x32_bf16 v[130:133], v[202:205], v[32:35], v[130:133]
	v_mfma_f32_16x16x32_bf16 v[134:137], v[206:209], v[36:39], 0
	v_mfma_f32_16x16x32_bf16 v[134:137], v[210:213], v[40:43], v[134:137]
	v_mfma_f32_16x16x32_bf16 v[134:137], v[214:217], v[44:47], v[134:137]
	v_mfma_f32_16x16x32_bf16 v[134:137], v[218:221], v[48:51], v[134:137]
	v_fma_f32 v108, v116, v126, v120
	v_fma_f32 v109, v117, v126, v121
	v_fma_f32 v110, v118, v126, v122
	v_fma_f32 v111, v119, v126, v123
	s_barrier
	s_nop 7
	v_fma_f32 v112, v130, v126, v134
	v_fma_f32 v113, v131, v126, v135
	v_fma_f32 v114, v132, v126, v136
	v_fma_f32 v115, v133, v126, v137
	v_lshl_or_b32 v117, v1, 2, v2
	v_lshlrev_b32_e32 v117, 2, v117
	v_and_b32_e32 v118, 3, v0
	v_lshrrev_b32_e32 v119, 2, v0
	v_lshl_or_b32 v116, v118, 4, v119
	v_lshlrev_b32_e32 v116, 2, v116
	v_mul_f32_e32 v4, v52, v52
	v_mul_f32_e32 v5, v53, v53
	v_mul_f32_e32 v6, v54, v54
	v_mul_f32_e32 v7, v55, v55
	v_fmac_f32_e32 v4, v56, v56
	v_fmac_f32_e32 v5, v57, v57
	v_fmac_f32_e32 v6, v58, v58
	v_fmac_f32_e32 v7, v59, v59
	v_fmac_f32_e32 v4, v60, v60
	v_fmac_f32_e32 v5, v61, v61
	v_fmac_f32_e32 v6, v62, v62
	v_fmac_f32_e32 v7, v63, v63
	v_fmac_f32_e32 v4, v64, v64
	v_fmac_f32_e32 v5, v65, v65
	v_fmac_f32_e32 v6, v66, v66
	v_fmac_f32_e32 v7, v67, v67
	v_fmac_f32_e32 v4, v68, v68
	v_fmac_f32_e32 v5, v69, v69
	v_fmac_f32_e32 v6, v70, v70
	v_fmac_f32_e32 v7, v71, v71
	v_fmac_f32_e32 v4, v72, v72
	v_fmac_f32_e32 v5, v73, v73
	v_fmac_f32_e32 v6, v74, v74
	v_fmac_f32_e32 v7, v75, v75
	v_fmac_f32_e32 v4, v76, v76
	v_fmac_f32_e32 v5, v77, v77
	v_fmac_f32_e32 v6, v78, v78
	v_fmac_f32_e32 v7, v79, v79
	v_fmac_f32_e32 v4, v80, v80
	v_fmac_f32_e32 v5, v81, v81
	v_fmac_f32_e32 v6, v82, v82
	v_fmac_f32_e32 v7, v83, v83
	v_fmac_f32_e32 v4, v84, v84
	v_fmac_f32_e32 v5, v85, v85
	v_fmac_f32_e32 v6, v86, v86
	v_fmac_f32_e32 v7, v87, v87
	v_fmac_f32_e32 v4, v88, v88
	v_fmac_f32_e32 v5, v89, v89
	v_fmac_f32_e32 v6, v90, v90
	v_fmac_f32_e32 v7, v91, v91
	v_fmac_f32_e32 v4, v92, v92
	v_fmac_f32_e32 v5, v93, v93
	v_fmac_f32_e32 v6, v94, v94
	v_fmac_f32_e32 v7, v95, v95
	v_fmac_f32_e32 v4, v96, v96
	v_fmac_f32_e32 v5, v97, v97
	v_fmac_f32_e32 v6, v98, v98
	v_fmac_f32_e32 v7, v99, v99
	v_fmac_f32_e32 v4, v100, v100
	v_fmac_f32_e32 v5, v101, v101
	v_fmac_f32_e32 v6, v102, v102
	v_fmac_f32_e32 v7, v103, v103
	v_fmac_f32_e32 v4, v104, v104
	v_fmac_f32_e32 v5, v105, v105
	v_fmac_f32_e32 v6, v106, v106
	v_fmac_f32_e32 v7, v107, v107
	v_fmac_f32_e32 v4, v108, v108
	v_fmac_f32_e32 v5, v109, v109
	v_fmac_f32_e32 v6, v110, v110
	v_fmac_f32_e32 v7, v111, v111
	v_fmac_f32_e32 v4, v112, v112
	v_fmac_f32_e32 v5, v113, v113
	v_fmac_f32_e32 v6, v114, v114
	v_fmac_f32_e32 v7, v115, v115
	v_add_f32_e32 v4, v4, v5
	v_add_f32_e32 v6, v6, v7
	v_add_f32_e32 v4, v4, v6
	s_nop 0
	ds_bpermute_b32 v5, v127, v4
	s_waitcnt lgkmcnt(0)
	v_add_f32_e32 v4, v4, v5
	s_nop 0
	ds_bpermute_b32 v5, v11, v4
	s_waitcnt lgkmcnt(0)
	v_add_f32_e32 v4, v4, v5
	v_mul_f32_e32 v4, 0x3b800000, v4
	v_add_f32_e32 v4, 0x358637bd, v4
	v_rsq_f32_e32 v10, v4
	s_waitcnt vmcnt(0)
	ds_bpermute_b32 v222, v117, v222
	ds_bpermute_b32 v223, v117, v223
	ds_bpermute_b32 v224, v117, v224
	ds_bpermute_b32 v225, v117, v225
	ds_bpermute_b32 v226, v117, v226
	ds_bpermute_b32 v227, v117, v227
	ds_bpermute_b32 v228, v117, v228
	ds_bpermute_b32 v229, v117, v229
	ds_bpermute_b32 v230, v117, v230
	ds_bpermute_b32 v231, v117, v231
	ds_bpermute_b32 v232, v117, v232
	ds_bpermute_b32 v233, v117, v233
	s_waitcnt lgkmcnt(0)
	ds_bpermute_b32 v236, v117, v236
	ds_bpermute_b32 v237, v117, v237
	ds_bpermute_b32 v238, v117, v238
	ds_bpermute_b32 v239, v117, v239
	ds_bpermute_b32 v240, v117, v240
	ds_bpermute_b32 v241, v117, v241
	ds_bpermute_b32 v242, v117, v242
	ds_bpermute_b32 v243, v117, v243
	ds_bpermute_b32 v244, v117, v244
	ds_bpermute_b32 v245, v117, v245
	ds_bpermute_b32 v246, v117, v246
	ds_bpermute_b32 v247, v117, v247
	s_waitcnt lgkmcnt(0)
	ds_bpermute_b32 v248, v117, v248
	ds_bpermute_b32 v249, v117, v249
	ds_bpermute_b32 v250, v117, v250
	ds_bpermute_b32 v251, v117, v251
	ds_bpermute_b32 v252, v117, v252
	ds_bpermute_b32 v253, v117, v253
	ds_bpermute_b32 v254, v117, v254
	ds_bpermute_b32 v255, v117, v255
	s_waitcnt lgkmcnt(0)
	v_lshlrev_b32_e32 v4, 16, v222
	v_and_b32_e32 v5, 0xffff0000, v222
	v_lshlrev_b32_e32 v6, 16, v223
	v_and_b32_e32 v7, 0xffff0000, v223
	v_mul_f32_e32 v52, v52, v10
	v_mul_f32_e32 v53, v53, v10
	v_mul_f32_e32 v54, v54, v10
	v_mul_f32_e32 v55, v55, v10
	v_mul_f32_e32 v52, v52, v4
	v_mul_f32_e32 v53, v53, v5
	v_mul_f32_e32 v54, v54, v6
	v_mul_f32_e32 v55, v55, v7
	v_cvt_pk_bf16_f32 v52, v52, v53
	v_cvt_pk_bf16_f32 v53, v54, v55
	v_lshlrev_b32_e32 v4, 16, v224
	v_and_b32_e32 v5, 0xffff0000, v224
	v_lshlrev_b32_e32 v6, 16, v225
	v_and_b32_e32 v7, 0xffff0000, v225
	v_mul_f32_e32 v56, v56, v10
	v_mul_f32_e32 v57, v57, v10
	v_mul_f32_e32 v58, v58, v10
	v_mul_f32_e32 v59, v59, v10
	v_mul_f32_e32 v56, v56, v4
	v_mul_f32_e32 v57, v57, v5
	v_mul_f32_e32 v58, v58, v6
	v_mul_f32_e32 v59, v59, v7
	v_cvt_pk_bf16_f32 v56, v56, v57
	v_cvt_pk_bf16_f32 v57, v58, v59
	v_lshlrev_b32_e32 v4, 16, v226
	v_and_b32_e32 v5, 0xffff0000, v226
	v_lshlrev_b32_e32 v6, 16, v227
	v_and_b32_e32 v7, 0xffff0000, v227
	v_mul_f32_e32 v60, v60, v10
	v_mul_f32_e32 v61, v61, v10
	v_mul_f32_e32 v62, v62, v10
	v_mul_f32_e32 v63, v63, v10
	v_mul_f32_e32 v60, v60, v4
	v_mul_f32_e32 v61, v61, v5
	v_mul_f32_e32 v62, v62, v6
	v_mul_f32_e32 v63, v63, v7
	v_cvt_pk_bf16_f32 v60, v60, v61
	v_cvt_pk_bf16_f32 v61, v62, v63
	v_lshlrev_b32_e32 v4, 16, v228
	v_and_b32_e32 v5, 0xffff0000, v228
	v_lshlrev_b32_e32 v6, 16, v229
	v_and_b32_e32 v7, 0xffff0000, v229
	v_mul_f32_e32 v64, v64, v10
	v_mul_f32_e32 v65, v65, v10
	v_mul_f32_e32 v66, v66, v10
	v_mul_f32_e32 v67, v67, v10
	v_mul_f32_e32 v64, v64, v4
	v_mul_f32_e32 v65, v65, v5
	v_mul_f32_e32 v66, v66, v6
	v_mul_f32_e32 v67, v67, v7
	v_cvt_pk_bf16_f32 v64, v64, v65
	v_cvt_pk_bf16_f32 v65, v66, v67
	v_lshlrev_b32_e32 v4, 16, v230
	v_and_b32_e32 v5, 0xffff0000, v230
	v_lshlrev_b32_e32 v6, 16, v231
	v_and_b32_e32 v7, 0xffff0000, v231
	v_mul_f32_e32 v68, v68, v10
	v_mul_f32_e32 v69, v69, v10
	v_mul_f32_e32 v70, v70, v10
	v_mul_f32_e32 v71, v71, v10
	v_mul_f32_e32 v68, v68, v4
	v_mul_f32_e32 v69, v69, v5
	v_mul_f32_e32 v70, v70, v6
	v_mul_f32_e32 v71, v71, v7
	v_cvt_pk_bf16_f32 v68, v68, v69
	v_cvt_pk_bf16_f32 v69, v70, v71
	v_lshlrev_b32_e32 v4, 16, v232
	v_and_b32_e32 v5, 0xffff0000, v232
	v_lshlrev_b32_e32 v6, 16, v233
	v_and_b32_e32 v7, 0xffff0000, v233
	v_mul_f32_e32 v72, v72, v10
	v_mul_f32_e32 v73, v73, v10
	v_mul_f32_e32 v74, v74, v10
	v_mul_f32_e32 v75, v75, v10
	v_mul_f32_e32 v72, v72, v4
	v_mul_f32_e32 v73, v73, v5
	v_mul_f32_e32 v74, v74, v6
	v_mul_f32_e32 v75, v75, v7
	v_cvt_pk_bf16_f32 v72, v72, v73
	v_cvt_pk_bf16_f32 v73, v74, v75
	v_lshlrev_b32_e32 v4, 16, v236
	v_and_b32_e32 v5, 0xffff0000, v236
	v_lshlrev_b32_e32 v6, 16, v237
	v_and_b32_e32 v7, 0xffff0000, v237
	v_mul_f32_e32 v76, v76, v10
	v_mul_f32_e32 v77, v77, v10
	v_mul_f32_e32 v78, v78, v10
	v_mul_f32_e32 v79, v79, v10
	v_mul_f32_e32 v76, v76, v4
	v_mul_f32_e32 v77, v77, v5
	v_mul_f32_e32 v78, v78, v6
	v_mul_f32_e32 v79, v79, v7
	v_cvt_pk_bf16_f32 v76, v76, v77
	v_cvt_pk_bf16_f32 v77, v78, v79
	v_lshlrev_b32_e32 v4, 16, v238
	v_and_b32_e32 v5, 0xffff0000, v238
	v_lshlrev_b32_e32 v6, 16, v239
	v_and_b32_e32 v7, 0xffff0000, v239
	v_mul_f32_e32 v80, v80, v10
	v_mul_f32_e32 v81, v81, v10
	v_mul_f32_e32 v82, v82, v10
	v_mul_f32_e32 v83, v83, v10
	v_mul_f32_e32 v80, v80, v4
	v_mul_f32_e32 v81, v81, v5
	v_mul_f32_e32 v82, v82, v6
	v_mul_f32_e32 v83, v83, v7
	v_cvt_pk_bf16_f32 v80, v80, v81
	v_cvt_pk_bf16_f32 v81, v82, v83
	v_lshlrev_b32_e32 v4, 16, v240
	v_and_b32_e32 v5, 0xffff0000, v240
	v_lshlrev_b32_e32 v6, 16, v241
	v_and_b32_e32 v7, 0xffff0000, v241
	v_mul_f32_e32 v84, v84, v10
	v_mul_f32_e32 v85, v85, v10
	v_mul_f32_e32 v86, v86, v10
	v_mul_f32_e32 v87, v87, v10
	v_mul_f32_e32 v84, v84, v4
	v_mul_f32_e32 v85, v85, v5
	v_mul_f32_e32 v86, v86, v6
	v_mul_f32_e32 v87, v87, v7
	v_cvt_pk_bf16_f32 v84, v84, v85
	v_cvt_pk_bf16_f32 v85, v86, v87
	v_lshlrev_b32_e32 v4, 16, v242
	v_and_b32_e32 v5, 0xffff0000, v242
	v_lshlrev_b32_e32 v6, 16, v243
	v_and_b32_e32 v7, 0xffff0000, v243
	v_mul_f32_e32 v88, v88, v10
	v_mul_f32_e32 v89, v89, v10
	v_mul_f32_e32 v90, v90, v10
	v_mul_f32_e32 v91, v91, v10
	v_mul_f32_e32 v88, v88, v4
	v_mul_f32_e32 v89, v89, v5
	v_mul_f32_e32 v90, v90, v6
	v_mul_f32_e32 v91, v91, v7
	v_cvt_pk_bf16_f32 v88, v88, v89
	v_cvt_pk_bf16_f32 v89, v90, v91
	v_lshlrev_b32_e32 v4, 16, v244
	v_and_b32_e32 v5, 0xffff0000, v244
	v_lshlrev_b32_e32 v6, 16, v245
	v_and_b32_e32 v7, 0xffff0000, v245
	v_mul_f32_e32 v92, v92, v10
	v_mul_f32_e32 v93, v93, v10
	v_mul_f32_e32 v94, v94, v10
	v_mul_f32_e32 v95, v95, v10
	v_mul_f32_e32 v92, v92, v4
	v_mul_f32_e32 v93, v93, v5
	v_mul_f32_e32 v94, v94, v6
	v_mul_f32_e32 v95, v95, v7
	v_cvt_pk_bf16_f32 v92, v92, v93
	v_cvt_pk_bf16_f32 v93, v94, v95
	v_lshlrev_b32_e32 v4, 16, v246
	v_and_b32_e32 v5, 0xffff0000, v246
	v_lshlrev_b32_e32 v6, 16, v247
	v_and_b32_e32 v7, 0xffff0000, v247
	v_mul_f32_e32 v96, v96, v10
	v_mul_f32_e32 v97, v97, v10
	v_mul_f32_e32 v98, v98, v10
	v_mul_f32_e32 v99, v99, v10
	v_mul_f32_e32 v96, v96, v4
	v_mul_f32_e32 v97, v97, v5
	v_mul_f32_e32 v98, v98, v6
	v_mul_f32_e32 v99, v99, v7
	v_cvt_pk_bf16_f32 v96, v96, v97
	v_cvt_pk_bf16_f32 v97, v98, v99
	v_lshlrev_b32_e32 v4, 16, v248
	v_and_b32_e32 v5, 0xffff0000, v248
	v_lshlrev_b32_e32 v6, 16, v249
	v_and_b32_e32 v7, 0xffff0000, v249
	v_mul_f32_e32 v100, v100, v10
	v_mul_f32_e32 v101, v101, v10
	v_mul_f32_e32 v102, v102, v10
	v_mul_f32_e32 v103, v103, v10
	v_mul_f32_e32 v100, v100, v4
	v_mul_f32_e32 v101, v101, v5
	v_mul_f32_e32 v102, v102, v6
	v_mul_f32_e32 v103, v103, v7
	v_cvt_pk_bf16_f32 v100, v100, v101
	v_cvt_pk_bf16_f32 v101, v102, v103
	v_lshlrev_b32_e32 v4, 16, v250
	v_and_b32_e32 v5, 0xffff0000, v250
	v_lshlrev_b32_e32 v6, 16, v251
	v_and_b32_e32 v7, 0xffff0000, v251
	v_mul_f32_e32 v104, v104, v10
	v_mul_f32_e32 v105, v105, v10
	v_mul_f32_e32 v106, v106, v10
	v_mul_f32_e32 v107, v107, v10
	v_mul_f32_e32 v104, v104, v4
	v_mul_f32_e32 v105, v105, v5
	v_mul_f32_e32 v106, v106, v6
	v_mul_f32_e32 v107, v107, v7
	v_cvt_pk_bf16_f32 v104, v104, v105
	v_cvt_pk_bf16_f32 v105, v106, v107
	v_lshlrev_b32_e32 v4, 16, v252
	v_and_b32_e32 v5, 0xffff0000, v252
	v_lshlrev_b32_e32 v6, 16, v253
	v_and_b32_e32 v7, 0xffff0000, v253
	v_mul_f32_e32 v108, v108, v10
	v_mul_f32_e32 v109, v109, v10
	v_mul_f32_e32 v110, v110, v10
	v_mul_f32_e32 v111, v111, v10
	v_mul_f32_e32 v108, v108, v4
	v_mul_f32_e32 v109, v109, v5
	v_mul_f32_e32 v110, v110, v6
	v_mul_f32_e32 v111, v111, v7
	v_cvt_pk_bf16_f32 v108, v108, v109
	v_cvt_pk_bf16_f32 v109, v110, v111
	v_lshlrev_b32_e32 v4, 16, v254
	v_and_b32_e32 v5, 0xffff0000, v254
	v_lshlrev_b32_e32 v6, 16, v255
	v_and_b32_e32 v7, 0xffff0000, v255
	v_mul_f32_e32 v112, v112, v10
	v_mul_f32_e32 v113, v113, v10
	v_mul_f32_e32 v114, v114, v10
	v_mul_f32_e32 v115, v115, v10
	v_mul_f32_e32 v112, v112, v4
	v_mul_f32_e32 v113, v113, v5
	v_mul_f32_e32 v114, v114, v6
	v_mul_f32_e32 v115, v115, v7
	v_cvt_pk_bf16_f32 v112, v112, v113
	v_cvt_pk_bf16_f32 v113, v114, v115
	ds_bpermute_b32 v52, v116, v52
	ds_bpermute_b32 v53, v116, v53
	ds_bpermute_b32 v56, v116, v56
	ds_bpermute_b32 v57, v116, v57
	ds_bpermute_b32 v60, v116, v60
	ds_bpermute_b32 v61, v116, v61
	ds_bpermute_b32 v64, v116, v64
	ds_bpermute_b32 v65, v116, v65
	ds_bpermute_b32 v68, v116, v68
	ds_bpermute_b32 v69, v116, v69
	ds_bpermute_b32 v72, v116, v72
	ds_bpermute_b32 v73, v116, v73
	s_waitcnt lgkmcnt(0)
	ds_bpermute_b32 v76, v116, v76
	ds_bpermute_b32 v77, v116, v77
	ds_bpermute_b32 v80, v116, v80
	ds_bpermute_b32 v81, v116, v81
	ds_bpermute_b32 v84, v116, v84
	ds_bpermute_b32 v85, v116, v85
	ds_bpermute_b32 v88, v116, v88
	ds_bpermute_b32 v89, v116, v89
	ds_bpermute_b32 v92, v116, v92
	ds_bpermute_b32 v93, v116, v93
	ds_bpermute_b32 v96, v116, v96
	ds_bpermute_b32 v97, v116, v97
	s_waitcnt lgkmcnt(0)
	ds_bpermute_b32 v100, v116, v100
	ds_bpermute_b32 v101, v116, v101
	ds_bpermute_b32 v104, v116, v104
	ds_bpermute_b32 v105, v116, v105
	ds_bpermute_b32 v108, v116, v108
	ds_bpermute_b32 v109, v116, v109
	ds_bpermute_b32 v112, v116, v112
	ds_bpermute_b32 v113, v116, v113
	s_waitcnt lgkmcnt(0)
	global_store_dwordx2 v124, v[52:53], s[74:75] offset:0
	global_store_dwordx2 v124, v[56:57], s[74:75] offset:32
	global_store_dwordx2 v124, v[60:61], s[74:75] offset:64
	global_store_dwordx2 v124, v[64:65], s[74:75] offset:96
	global_store_dwordx2 v124, v[68:69], s[74:75] offset:128
	global_store_dwordx2 v124, v[72:73], s[74:75] offset:160
	global_store_dwordx2 v124, v[76:77], s[74:75] offset:192
	global_store_dwordx2 v124, v[80:81], s[74:75] offset:224
	global_store_dwordx2 v124, v[84:85], s[74:75] offset:256
	global_store_dwordx2 v124, v[88:89], s[74:75] offset:288
	global_store_dwordx2 v124, v[92:93], s[74:75] offset:320
	global_store_dwordx2 v124, v[96:97], s[74:75] offset:352
	global_store_dwordx2 v124, v[100:101], s[74:75] offset:384
	global_store_dwordx2 v124, v[104:105], s[74:75] offset:416
	global_store_dwordx2 v124, v[108:109], s[74:75] offset:448
	global_store_dwordx2 v124, v[112:113], s[74:75] offset:480
	s_add_u32 s64, s64, s94
	s_cmp_lt_u32 s64, 0x200
	s_cbranch_scc1 .LR3_unit
